# wave-to-subtile remap (wn from tid bit7) + GEMM K-loops: fragment reads pipelined one MFMA group ahead, LDS-DMA issue threaded through MFMAs
# speedup vs baseline: 1.0599x; 1.0331x over previous
.LBB0_210:
	s_mul_hi_i32 s8, s10, 0x3e0f83e1
	s_lshr_b32 s9, s8, 31
	s_ashr_i32 s92, s8, 3
	s_add_i32 s92, s92, s9
	s_lshl_b32 s93, s10, 8
	s_mul_i32 s8, s92, 0xffffdf00
	s_add_i32 s40, s8, s93
	s_andn2_b64 vcc, exec, s[0:1]
	s_mov_b64 s[0:1], -1
	s_cbranch_vccnz .LBB0_246
	v_mov_b32_e32 v20, v190
	s_and_b32 s95, s94, 7
	s_lshl_b32 s10, s95, 8
	v_ashrrev_i32_e32 v16, 3, v20
	v_lshrrev_b32_e32 v21, 4, v20
	v_add_u32_e32 v23, s93, v16
	v_xor_b32_e32 v22, v21, v20
	v_add_u32_e32 v6, 64, v23
	v_mov_b64_e32 v[4:5], s[18:19]
	v_add_u32_e32 v10, 0x80, v23
	v_add_u32_e32 v14, 0xc0, v23
	v_add_u32_e32 v24, s10, v16
	v_mov_b64_e32 v[18:19], s[20:21]
	v_mad_i64_i32 v[0:1], s[0:1], v23, s78, 0
	v_mad_i64_i32 v[2:3], s[0:1], v6, s78, 0
	v_mad_i64_i32 v[6:7], s[0:1], v6, s78, v[4:5]
	v_mad_i64_i32 v[8:9], s[0:1], v10, s78, 0
	v_mad_i64_i32 v[10:11], s[0:1], v10, s78, v[4:5]
	v_mad_i64_i32 v[12:13], s[0:1], v14, s78, 0
	v_mad_i64_i32 v[14:15], s[0:1], v14, s78, v[4:5]
	v_mad_i64_i32 v[16:17], s[0:1], v24, s78, 0
	v_mad_i64_i32 v[18:19], s[0:1], v24, s78, v[18:19]
	v_mad_i64_i32 v[4:5], s[0:1], v23, s78, v[4:5]
	v_lshlrev_b32_e32 v22, 4, v22
	v_lshl_add_u32 v152, v20, 4, 0
	v_and_b32_e32 v176, 0x70, v22
	v_readfirstlane_b32 s0, v152
	v_lshl_add_u64 v[4:5], v[4:5], 0, v[176:177]
	s_mov_b32 m0, s0
	v_lshl_add_u64 v[6:7], v[6:7], 0, v[176:177]
	global_load_lds_dwordx4 v[4:5], off
	v_add_u32_e32 v4, 0x2000, v152
	v_lshl_add_u64 v[10:11], v[10:11], 0, v[176:177]
	v_readfirstlane_b32 s0, v4
	v_add_u32_e32 v4, 0x4000, v152
	s_mov_b32 m0, s0
	v_readfirstlane_b32 s0, v4
	v_add_u32_e32 v4, 0x6000, v152
	global_load_lds_dwordx4 v[6:7], off
	s_mov_b32 m0, s0
	v_readfirstlane_b32 s0, v4
	v_add_u32_e32 v4, 0x8000, v152
	v_lshl_add_u64 v[14:15], v[14:15], 0, v[176:177]
	global_load_lds_dwordx4 v[10:11], off
	s_mov_b32 m0, s0
	v_readfirstlane_b32 s0, v4
	v_lshl_add_u64 v[18:19], v[18:19], 0, v[176:177]
	global_load_lds_dwordx4 v[14:15], off
	s_mov_b32 m0, s0
	s_mov_b64 s[0:1], 0x22000
	v_add_u32_e32 v6, 0xa000, v152
	v_lshl_add_u64 v[4:5], v[18:19], 0, s[0:1]
	v_readfirstlane_b32 s0, v6
	global_load_lds_dwordx4 v[18:19], off
	s_mov_b32 m0, s0
	s_mov_b64 s[0:1], 0x44000
	v_add_u32_e32 v6, 0xc000, v152
	global_load_lds_dwordx4 v[4:5], off
	v_lshl_add_u64 v[4:5], v[18:19], 0, s[0:1]
	v_readfirstlane_b32 s0, v6
	s_mov_b32 m0, s0
	s_mov_b64 s[0:1], 0x66000
	v_add_u32_e32 v6, 0xe000, v152
	global_load_lds_dwordx4 v[4:5], off
	v_lshl_add_u64 v[4:5], v[18:19], 0, s[0:1]
	v_readfirstlane_b32 s0, v6
	s_mov_b32 m0, s0
	v_and_b32_e32 v147, 15, v20
	global_load_lds_dwordx4 v[4:5], off
	v_bfe_u32 v148, v20, 4, 2
	v_bfe_u32 v22, v20, 1, 3
	v_lshlrev_b32_e32 v23, 7, v147
	v_bitop3_b32 v24, v21, v22, 3 bitop3:0x6c
	v_bitop3_b32 v22, v148, v22, 4 bitop3:0x36
	v_bitop3_b32 v4, v21, 7, v20 bitop3:0x48
	v_lshl_or_b32 v150, v22, 4, v23
	v_ashrrev_i32_e32 v22, 1, v20
	v_lshlrev_b32_e32 v4, 4, v4
	v_bfe_u32 v146, v20, 7, 1
	v_and_b32_e32 v149, 0xffffff80, v22
	v_and_or_b32 v149, v20, 64, v149
	v_or_b32_e32 v16, v16, v4
	v_or_b32_e32 v12, v12, v4
	v_or_b32_e32 v8, v8, v4
	v_or_b32_e32 v2, v2, v4
	v_or_b32_e32 v0, v0, v4
	v_mov_b32_e32 v108, 0
	v_lshl_or_b32 v151, v24, 4, v23
	v_lshl_add_u64 v[128:129], s[62:63], 0, v[16:17]
	v_lshl_add_u64 v[130:131], s[64:65], 0, v[12:13]
	v_lshl_add_u64 v[132:133], s[64:65], 0, v[8:9]
	v_lshl_add_u64 v[134:135], s[64:65], 0, v[2:3]
	v_lshl_add_u64 v[144:145], s[64:65], 0, v[0:1]
	s_mov_b32 s0, 0
	s_mov_b64 s[8:9], 0
	v_mov_b32_e32 v109, v108
	v_mov_b32_e32 v110, v108
	v_mov_b32_e32 v111, v108
	v_mov_b32_e32 v0, v108
	v_mov_b32_e32 v1, v108
	v_mov_b32_e32 v2, v108
	v_mov_b32_e32 v3, v108
	v_mov_b32_e32 v4, v108
	v_mov_b32_e32 v5, v108
	v_mov_b32_e32 v6, v108
	v_mov_b32_e32 v7, v108
	v_mov_b32_e32 v8, v108
	v_mov_b32_e32 v9, v108
	v_mov_b32_e32 v10, v108
	v_mov_b32_e32 v11, v108
	v_mov_b32_e32 v16, v108
	v_mov_b32_e32 v17, v108
	v_mov_b32_e32 v18, v108
	v_mov_b32_e32 v19, v108
	v_mov_b32_e32 v24, v108
	v_mov_b32_e32 v25, v108
	v_mov_b32_e32 v26, v108
	v_mov_b32_e32 v27, v108
	v_mov_b32_e32 v32, v108
	v_mov_b32_e32 v33, v108
	v_mov_b32_e32 v34, v108
	v_mov_b32_e32 v35, v108
	v_mov_b32_e32 v40, v108
	v_mov_b32_e32 v41, v108
	v_mov_b32_e32 v42, v108
	v_mov_b32_e32 v43, v108
	v_mov_b32_e32 v12, v108
	v_mov_b32_e32 v13, v108
	v_mov_b32_e32 v14, v108
	v_mov_b32_e32 v15, v108
	v_mov_b32_e32 v20, v108
	v_mov_b32_e32 v21, v108
	v_mov_b32_e32 v22, v108
	v_mov_b32_e32 v23, v108
	v_mov_b32_e32 v28, v108
	v_mov_b32_e32 v29, v108
	v_mov_b32_e32 v30, v108
	v_mov_b32_e32 v31, v108
	v_mov_b32_e32 v36, v108
	v_mov_b32_e32 v37, v108
	v_mov_b32_e32 v38, v108
	v_mov_b32_e32 v39, v108
	v_mov_b32_e32 v48, v108
	v_mov_b32_e32 v49, v108
	v_mov_b32_e32 v50, v108
	v_mov_b32_e32 v51, v108
	v_mov_b32_e32 v56, v108
	v_mov_b32_e32 v57, v108
	v_mov_b32_e32 v58, v108
	v_mov_b32_e32 v59, v108
	v_mov_b32_e32 v64, v108
	v_mov_b32_e32 v65, v108
	v_mov_b32_e32 v66, v108
	v_mov_b32_e32 v67, v108
	v_mov_b32_e32 v72, v108
	v_mov_b32_e32 v73, v108
	v_mov_b32_e32 v74, v108
	v_mov_b32_e32 v75, v108
	v_mov_b32_e32 v44, v108
	v_mov_b32_e32 v45, v108
	v_mov_b32_e32 v46, v108
	v_mov_b32_e32 v47, v108
	v_mov_b32_e32 v52, v108
	v_mov_b32_e32 v53, v108
	v_mov_b32_e32 v54, v108
	v_mov_b32_e32 v55, v108
	v_mov_b32_e32 v60, v108
	v_mov_b32_e32 v61, v108
	v_mov_b32_e32 v62, v108
	v_mov_b32_e32 v63, v108
	v_mov_b32_e32 v68, v108
	v_mov_b32_e32 v69, v108
	v_mov_b32_e32 v70, v108
	v_mov_b32_e32 v71, v108
	v_mov_b32_e32 v80, v108
	v_mov_b32_e32 v81, v108
	v_mov_b32_e32 v82, v108
	v_mov_b32_e32 v83, v108
	v_mov_b32_e32 v88, v108
	v_mov_b32_e32 v89, v108
	v_mov_b32_e32 v90, v108
	v_mov_b32_e32 v91, v108
	v_mov_b32_e32 v96, v108
	v_mov_b32_e32 v97, v108
	v_mov_b32_e32 v98, v108
	v_mov_b32_e32 v99, v108
	v_mov_b32_e32 v104, v108
	v_mov_b32_e32 v105, v108
	v_mov_b32_e32 v106, v108
	v_mov_b32_e32 v107, v108
	v_mov_b32_e32 v76, v108
	v_mov_b32_e32 v77, v108
	v_mov_b32_e32 v78, v108
	v_mov_b32_e32 v79, v108
	v_mov_b32_e32 v84, v108
	v_mov_b32_e32 v85, v108
	v_mov_b32_e32 v86, v108
	v_mov_b32_e32 v87, v108
	v_mov_b32_e32 v92, v108
	v_mov_b32_e32 v93, v108
	v_mov_b32_e32 v94, v108
	v_mov_b32_e32 v95, v108
	v_mov_b32_e32 v100, v108
	v_mov_b32_e32 v101, v108
	v_mov_b32_e32 v102, v108
	v_mov_b32_e32 v103, v108
	v_mov_b32_e32 v112, v108
	v_mov_b32_e32 v113, v108
	v_mov_b32_e32 v114, v108
	v_mov_b32_e32 v115, v108
	v_mov_b32_e32 v116, v108
	v_mov_b32_e32 v117, v108
	v_mov_b32_e32 v118, v108
	v_mov_b32_e32 v119, v108
	v_mov_b32_e32 v120, v108
	v_mov_b32_e32 v121, v108
	v_mov_b32_e32 v122, v108
	v_mov_b32_e32 v123, v108
	v_mov_b32_e32 v124, v108
	v_mov_b32_e32 v125, v108
	v_mov_b32_e32 v126, v108
	v_mov_b32_e32 v127, v108
	v_lshlrev_b32_e32 v153, 7, v149
	v_lshlrev_b32_e32 v154, 14, v146
.LBB0_212:
	s_add_i32 s1, s0, 0x10000
	s_and_b32 s11, s1, 0x10000
	s_waitcnt vmcnt(0)
	s_barrier
	s_and_b32 s0, s0, 0x10000
	s_add_i32 s0, s0, 0
	v_add_u32_e32 v155, s0, v153
	v_add_u32_e32 v164, v155, v151
	ds_read_b128 v[156:159], v164
	ds_read_b128 v[160:163], v164 offset:2048
	ds_read_b128 v[178:181], v164 offset:4096
	ds_read_b128 v[182:185], v164 offset:6144
	v_add_u32_e32 v249, v155, v150
	v_add_u32_e32 v164, s0, v154
	v_add_u32_e32 v165, v164, v151
	ds_read_b128 v[186:189], v165 offset:32768
	ds_read_b128 v[192:195], v165 offset:34816
	ds_read_b128 v[198:201], v165 offset:36864
	ds_read_b128 v[204:207], v165 offset:38912
	v_add_u32_e32 v248, v164, v150
	ds_read_b128 v[224:227], v165 offset:40960
	ds_read_b128 v[228:231], v165 offset:43008
	ds_read_b128 v[232:235], v165 offset:45056
	ds_read_b128 v[236:239], v165 offset:47104
	v_add_u32_e32 v251, s11, v152
	v_add_u32_e32 v240, 0x2000, v251
	v_readfirstlane_b32 s11, v251
	v_lshl_add_u64 v[174:175], v[144:145], 0, s[8:9]
	s_mov_b32 m0, s11
	v_readfirstlane_b32 s11, v240
	v_add_u32_e32 v240, 0x4000, v251
	global_load_lds_dwordx4 v[174:175], off
	v_lshl_add_u64 v[174:175], v[134:135], 0, s[8:9]
	s_mov_b32 m0, s11
	s_waitcnt lgkmcnt(4)
	v_mfma_f32_16x16x32_bf16 v[124:127], v[156:159], v[186:189], v[124:127]
	ds_read_b128 v[208:211], v249
	v_mfma_f32_16x16x32_bf16 v[120:123], v[156:159], v[192:195], v[120:123]
	ds_read_b128 v[212:215], v249 offset:2048
	v_readfirstlane_b32 s11, v240
	v_add_u32_e32 v240, 0x6000, v251
	global_load_lds_dwordx4 v[174:175], off
	v_mfma_f32_16x16x32_bf16 v[116:119], v[156:159], v[198:201], v[116:119]
	ds_read_b128 v[216:219], v249 offset:4096
	v_lshl_add_u64 v[174:175], v[132:133], 0, s[8:9]
	s_mov_b32 m0, s11
	v_readfirstlane_b32 s11, v240
	v_mfma_f32_16x16x32_bf16 v[112:115], v[156:159], v[204:207], v[112:115]
	ds_read_b128 v[220:223], v249 offset:6144
	global_load_lds_dwordx4 v[174:175], off
	v_lshl_add_u64 v[174:175], v[130:131], 0, s[8:9]
	s_mov_b32 m0, s11
	v_mfma_f32_16x16x32_bf16 v[104:107], v[160:163], v[186:189], v[104:107]
	v_add_u32_e32 v250, 0x8000, v251
	global_load_lds_dwordx4 v[174:175], off
	v_lshl_add_u64 v[174:175], v[128:129], 0, s[8:9]
	v_mfma_f32_16x16x32_bf16 v[96:99], v[160:163], v[192:195], v[96:99]
	v_readfirstlane_b32 s11, v250
	v_add_u32_e32 v250, 0xa000, v251
	v_lshl_add_u64 v[240:241], v[174:175], 0, s[66:67]
	v_mfma_f32_16x16x32_bf16 v[88:91], v[160:163], v[198:201], v[88:91]
	s_mov_b32 m0, s11
	s_mov_b64 s[12:13], 0x22080
	v_readfirstlane_b32 s11, v250
	v_mfma_f32_16x16x32_bf16 v[80:83], v[160:163], v[204:207], v[80:83]
	v_add_u32_e32 v250, 0xc000, v251
	global_load_lds_dwordx4 v[240:241], off
	v_lshl_add_u64 v[240:241], v[174:175], 0, s[12:13]
	v_mfma_f32_16x16x32_bf16 v[72:75], v[178:181], v[186:189], v[72:75]
	s_mov_b32 m0, s11
	s_mov_b64 s[12:13], 0x44080
	v_readfirstlane_b32 s11, v250
	v_mfma_f32_16x16x32_bf16 v[64:67], v[178:181], v[192:195], v[64:67]
	v_add_u32_e32 v251, 0xe000, v251
	global_load_lds_dwordx4 v[240:241], off
	v_lshl_add_u64 v[240:241], v[174:175], 0, s[12:13]
	v_mfma_f32_16x16x32_bf16 v[56:59], v[178:181], v[198:201], v[56:59]
	s_mov_b32 m0, s11
	s_mov_b64 s[12:13], 0x66080
	v_readfirstlane_b32 s11, v251
	v_mfma_f32_16x16x32_bf16 v[48:51], v[178:181], v[204:207], v[48:51]
	global_load_lds_dwordx4 v[240:241], off
	v_lshl_add_u64 v[174:175], v[174:175], 0, s[12:13]
	s_mov_b32 m0, s11
	v_mfma_f32_16x16x32_bf16 v[40:43], v[182:185], v[186:189], v[40:43]
	global_load_lds_dwordx4 v[174:175], off
	v_mfma_f32_16x16x32_bf16 v[32:35], v[182:185], v[192:195], v[32:35]
	v_mfma_f32_16x16x32_bf16 v[24:27], v[182:185], v[198:201], v[24:27]
	v_mfma_f32_16x16x32_bf16 v[16:19], v[182:185], v[204:207], v[16:19]
	s_waitcnt lgkmcnt(4)
	v_mfma_f32_16x16x32_bf16 v[100:103], v[156:159], v[224:227], v[100:103]
	v_mfma_f32_16x16x32_bf16 v[92:95], v[156:159], v[228:231], v[92:95]
	v_mfma_f32_16x16x32_bf16 v[84:87], v[156:159], v[232:235], v[84:87]
	ds_read_b128 v[186:189], v248 offset:32768
	v_mfma_f32_16x16x32_bf16 v[76:79], v[156:159], v[236:239], v[76:79]
	ds_read_b128 v[192:195], v248 offset:34816
	v_mfma_f32_16x16x32_bf16 v[68:71], v[160:163], v[224:227], v[68:71]
	ds_read_b128 v[198:201], v248 offset:36864
	v_mfma_f32_16x16x32_bf16 v[60:63], v[160:163], v[228:231], v[60:63]
	ds_read_b128 v[204:207], v248 offset:38912
	v_mfma_f32_16x16x32_bf16 v[52:55], v[160:163], v[232:235], v[52:55]
	v_mfma_f32_16x16x32_bf16 v[44:47], v[160:163], v[236:239], v[44:47]
	v_mfma_f32_16x16x32_bf16 v[36:39], v[178:181], v[224:227], v[36:39]
	v_mfma_f32_16x16x32_bf16 v[28:31], v[178:181], v[228:231], v[28:31]
	v_mfma_f32_16x16x32_bf16 v[20:23], v[178:181], v[232:235], v[20:23]
	v_mfma_f32_16x16x32_bf16 v[12:15], v[178:181], v[236:239], v[12:15]
	v_mfma_f32_16x16x32_bf16 v[8:11], v[182:185], v[224:227], v[8:11]
	v_mfma_f32_16x16x32_bf16 v[4:7], v[182:185], v[228:231], v[4:7]
	v_mfma_f32_16x16x32_bf16 v[0:3], v[182:185], v[232:235], v[0:3]
	v_mfma_f32_16x16x32_bf16 v[108:111], v[182:185], v[236:239], v[108:111]
	s_waitcnt lgkmcnt(0)
	v_mfma_f32_16x16x32_bf16 v[124:127], v[208:211], v[186:189], v[124:127]
	ds_read_b128 v[224:227], v248 offset:40960
	v_mfma_f32_16x16x32_bf16 v[120:123], v[208:211], v[192:195], v[120:123]
	ds_read_b128 v[228:231], v248 offset:43008
	v_mfma_f32_16x16x32_bf16 v[116:119], v[208:211], v[198:201], v[116:119]
	ds_read_b128 v[232:235], v248 offset:45056
	v_mfma_f32_16x16x32_bf16 v[112:115], v[208:211], v[204:207], v[112:115]
	ds_read_b128 v[236:239], v248 offset:47104
	v_mfma_f32_16x16x32_bf16 v[104:107], v[212:215], v[186:189], v[104:107]
	v_mfma_f32_16x16x32_bf16 v[96:99], v[212:215], v[192:195], v[96:99]
	v_mfma_f32_16x16x32_bf16 v[88:91], v[212:215], v[198:201], v[88:91]
	v_mfma_f32_16x16x32_bf16 v[80:83], v[212:215], v[204:207], v[80:83]
	v_mfma_f32_16x16x32_bf16 v[72:75], v[216:219], v[186:189], v[72:75]
	v_mfma_f32_16x16x32_bf16 v[64:67], v[216:219], v[192:195], v[64:67]
	v_mfma_f32_16x16x32_bf16 v[56:59], v[216:219], v[198:201], v[56:59]
	v_mfma_f32_16x16x32_bf16 v[48:51], v[216:219], v[204:207], v[48:51]
	v_mfma_f32_16x16x32_bf16 v[40:43], v[220:223], v[186:189], v[40:43]
	v_mfma_f32_16x16x32_bf16 v[32:35], v[220:223], v[192:195], v[32:35]
	v_mfma_f32_16x16x32_bf16 v[24:27], v[220:223], v[198:201], v[24:27]
	v_mfma_f32_16x16x32_bf16 v[16:19], v[220:223], v[204:207], v[16:19]
	s_waitcnt lgkmcnt(0)
	v_mfma_f32_16x16x32_bf16 v[100:103], v[208:211], v[224:227], v[100:103]
	v_mfma_f32_16x16x32_bf16 v[92:95], v[208:211], v[228:231], v[92:95]
	v_mfma_f32_16x16x32_bf16 v[84:87], v[208:211], v[232:235], v[84:87]
	v_mfma_f32_16x16x32_bf16 v[76:79], v[208:211], v[236:239], v[76:79]
	v_mfma_f32_16x16x32_bf16 v[68:71], v[212:215], v[224:227], v[68:71]
	v_mfma_f32_16x16x32_bf16 v[60:63], v[212:215], v[228:231], v[60:63]
	v_mfma_f32_16x16x32_bf16 v[52:55], v[212:215], v[232:235], v[52:55]
	v_mfma_f32_16x16x32_bf16 v[44:47], v[212:215], v[236:239], v[44:47]
	v_mfma_f32_16x16x32_bf16 v[36:39], v[216:219], v[224:227], v[36:39]
	v_mfma_f32_16x16x32_bf16 v[28:31], v[216:219], v[228:231], v[28:31]
	v_mfma_f32_16x16x32_bf16 v[20:23], v[216:219], v[232:235], v[20:23]
	v_mfma_f32_16x16x32_bf16 v[12:15], v[216:219], v[236:239], v[12:15]
	s_add_u32 s8, s8, 0x80
	s_addc_u32 s9, s9, 0
	s_cmpk_eq_i32 s8, 0x780
	s_mov_b32 s0, s1
	v_mfma_f32_16x16x32_bf16 v[8:11], v[220:223], v[224:227], v[8:11]
	v_mfma_f32_16x16x32_bf16 v[4:7], v[220:223], v[228:231], v[4:7]
	v_mfma_f32_16x16x32_bf16 v[0:3], v[220:223], v[232:235], v[0:3]
	v_mfma_f32_16x16x32_bf16 v[108:111], v[220:223], v[236:239], v[108:111]
	s_cbranch_scc0 .LBB0_212
	s_add_i32 s0, 0, 0x10000
	v_add_u32_e32 v144, s0, v154
	v_add_u32_e32 v162, s0, v153
	v_add_u32_e32 v145, v144, v151
	v_add_u32_e32 v151, v162, v151
	s_waitcnt vmcnt(0)
	s_barrier
	ds_read_b128 v[128:131], v145 offset:38912
	ds_read_b128 v[132:135], v145 offset:36864
	ds_read_b128 v[154:157], v145 offset:34816
	ds_read_b128 v[158:161], v145 offset:32768
	ds_read_b128 v[178:181], v151 offset:6144
	ds_read_b128 v[182:185], v151 offset:4096
	ds_read_b128 v[186:189], v151 offset:2048
	ds_read_b128 v[204:207], v151
	s_waitcnt lgkmcnt(0)
	v_mfma_f32_16x16x32_bf16 v[124:127], v[204:207], v[158:161], v[124:127]
	v_mfma_f32_16x16x32_bf16 v[120:123], v[204:207], v[154:157], v[120:123]
	v_mfma_f32_16x16x32_bf16 v[116:119], v[204:207], v[132:135], v[116:119]
	v_mfma_f32_16x16x32_bf16 v[112:115], v[204:207], v[128:131], v[112:115]
	v_mfma_f32_16x16x32_bf16 v[104:107], v[186:189], v[158:161], v[104:107]
	v_mfma_f32_16x16x32_bf16 v[72:75], v[182:185], v[158:161], v[72:75]
	v_mfma_f32_16x16x32_bf16 v[64:67], v[182:185], v[154:157], v[64:67]
	v_mfma_f32_16x16x32_bf16 v[56:59], v[182:185], v[132:135], v[56:59]
	v_mfma_f32_16x16x32_bf16 v[48:51], v[182:185], v[128:131], v[48:51]
	v_mfma_f32_16x16x32_bf16 v[208:211], v[186:189], v[154:157], v[96:99]
	v_mfma_f32_16x16x32_bf16 v[212:215], v[186:189], v[132:135], v[88:91]
	v_mfma_f32_16x16x32_bf16 v[216:219], v[186:189], v[128:131], v[80:83]
	v_mfma_f32_16x16x32_bf16 v[158:161], v[178:181], v[158:161], v[40:43]
	v_mfma_f32_16x16x32_bf16 v[152:155], v[178:181], v[154:157], v[32:35]
	v_mfma_f32_16x16x32_bf16 v[132:135], v[178:181], v[132:135], v[24:27]
	v_mfma_f32_16x16x32_bf16 v[128:131], v[178:181], v[128:131], v[16:19]
	s_nop 2
	ds_read_b128 v[16:19], v145 offset:40960
	ds_read_b128 v[24:27], v145 offset:43008
	ds_read_b128 v[32:35], v145 offset:45056
	ds_read_b128 v[40:43], v145 offset:47104
	s_waitcnt lgkmcnt(0)
	v_mfma_f32_16x16x32_bf16 v[100:103], v[204:207], v[16:19], v[100:103]
	v_mfma_f32_16x16x32_bf16 v[92:95], v[204:207], v[24:27], v[92:95]
	v_mfma_f32_16x16x32_bf16 v[220:223], v[204:207], v[32:35], v[84:87]
	v_mfma_f32_16x16x32_bf16 v[76:79], v[204:207], v[40:43], v[76:79]
	v_mfma_f32_16x16x32_bf16 v[68:71], v[186:189], v[16:19], v[68:71]
	v_mfma_f32_16x16x32_bf16 v[60:63], v[186:189], v[24:27], v[60:63]
	v_mfma_f32_16x16x32_bf16 v[204:207], v[186:189], v[32:35], v[52:55]
	v_mfma_f32_16x16x32_bf16 v[44:47], v[186:189], v[40:43], v[44:47]
	v_mfma_f32_16x16x32_bf16 v[186:189], v[182:185], v[16:19], v[36:39]
	v_mfma_f32_16x16x32_bf16 v[224:227], v[182:185], v[24:27], v[28:31]
	v_mfma_f32_16x16x32_bf16 v[228:231], v[182:185], v[32:35], v[20:23]
	v_mfma_f32_16x16x32_bf16 v[182:185], v[182:185], v[40:43], v[12:15]
	v_mfma_f32_16x16x32_bf16 v[232:235], v[178:181], v[16:19], v[8:11]
	v_mfma_f32_16x16x32_bf16 v[236:239], v[178:181], v[24:27], v[4:7]
	v_mfma_f32_16x16x32_bf16 v[240:243], v[178:181], v[32:35], v[0:3]
	v_mfma_f32_16x16x32_bf16 v[244:247], v[178:181], v[40:43], v[108:111]
	s_nop 1
	v_add_u32_e32 v0, v162, v150
	v_add_u32_e32 v144, v144, v150
	ds_read_b128 v[108:111], v0
	ds_read_b128 v[178:181], v0 offset:2048
	ds_read_b128 v[248:251], v0 offset:4096
	ds_read_b128 v[192:195], v0 offset:6144
	ds_read_b128 v[0:3], v144 offset:32768
	ds_read_b128 v[4:7], v144 offset:34816
	ds_read_b128 v[198:201], v144 offset:36864
	ds_read_b128 v[162:165], v144 offset:38912
	s_waitcnt lgkmcnt(0)
	v_mfma_f32_16x16x32_bf16 v[88:91], v[108:111], v[0:3], v[124:127]
	v_mfma_f32_16x16x32_bf16 v[96:99], v[108:111], v[4:7], v[120:123]
	v_mfma_f32_16x16x32_bf16 v[80:83], v[108:111], v[198:201], v[116:119]
	v_mfma_f32_16x16x32_bf16 v[84:87], v[108:111], v[162:165], v[112:115]
	v_mfma_f32_16x16x32_bf16 v[40:43], v[178:181], v[0:3], v[104:107]
	v_mfma_f32_16x16x32_bf16 v[52:55], v[178:181], v[4:7], v[208:211]
	v_mfma_f32_16x16x32_bf16 v[32:35], v[178:181], v[198:201], v[212:215]
	v_mfma_f32_16x16x32_bf16 v[36:39], v[178:181], v[162:165], v[216:219]
	v_mfma_f32_16x16x32_bf16 v[24:27], v[248:251], v[0:3], v[72:75]
	v_mfma_f32_16x16x32_bf16 v[28:31], v[248:251], v[4:7], v[64:67]
	v_mfma_f32_16x16x32_bf16 v[16:19], v[248:251], v[198:201], v[56:59]
	v_mfma_f32_16x16x32_bf16 v[20:23], v[248:251], v[162:165], v[48:51]
	v_mfma_f32_16x16x32_bf16 v[8:11], v[192:195], v[0:3], v[158:161]
	v_mfma_f32_16x16x32_bf16 v[12:15], v[192:195], v[4:7], v[152:155]
	v_mfma_f32_16x16x32_bf16 v[0:3], v[192:195], v[198:201], v[132:135]
	v_mfma_f32_16x16x32_bf16 v[4:7], v[192:195], v[162:165], v[128:131]
	ds_read_b128 v[48:51], v144 offset:40960
	ds_read_b128 v[64:67], v144 offset:43008
	s_nop 0
	ds_read_b128 v[128:131], v144 offset:45056
	ds_read_b128 v[132:135], v144 offset:47104
	s_waitcnt lgkmcnt(0)
	v_mfma_f32_16x16x32_bf16 v[104:107], v[178:181], v[48:51], v[68:71]
	v_cmp_ne_u32_e64 s[8:9], 0, v146
	v_cmp_eq_u32_e32 vcc, 0, v146
	s_waitcnt vmcnt(0)
	v_lshl_or_b32 v68, v148, 2, v149
	v_lshl_add_u32 v69, v147, 2, 0
	v_mfma_f32_16x16x32_bf16 v[120:123], v[108:111], v[48:51], v[100:103]
	s_barrier
	v_mfma_f32_16x16x32_bf16 v[124:127], v[108:111], v[64:67], v[92:95]
	v_mfma_f32_16x16x32_bf16 v[112:115], v[108:111], v[128:131], v[220:223]
	v_mfma_f32_16x16x32_bf16 v[116:119], v[108:111], v[132:135], v[76:79]
	v_mfma_f32_16x16x32_bf16 v[108:111], v[178:181], v[64:67], v[60:63]
	v_mfma_f32_16x16x32_bf16 v[92:95], v[178:181], v[128:131], v[204:207]
	v_mfma_f32_16x16x32_bf16 v[100:103], v[178:181], v[132:135], v[44:47]
	v_mfma_f32_16x16x32_bf16 v[56:59], v[248:251], v[48:51], v[186:189]
	v_mfma_f32_16x16x32_bf16 v[60:63], v[248:251], v[64:67], v[224:227]
	v_mfma_f32_16x16x32_bf16 v[44:47], v[248:251], v[128:131], v[228:231]
	v_mfma_f32_16x16x32_bf16 v[72:75], v[248:251], v[132:135], v[182:185]
	v_mfma_f32_16x16x32_bf16 v[48:51], v[192:195], v[48:51], v[232:235]
	s_nop 1
	v_lshl_add_u32 v182, v68, 9, v69
	v_add_u32_e32 v183, 0x400, v182
	v_add_u32_e32 v181, 0x2000, v182
	v_mfma_f32_16x16x32_bf16 v[64:67], v[192:195], v[64:67], v[236:239]
	v_add_u32_e32 v180, 0x2400, v182
	v_add_u32_e32 v179, 0x4000, v182
	v_add_u32_e32 v178, 0x4400, v182
	v_mfma_f32_16x16x32_bf16 v[68:71], v[192:195], v[128:131], v[240:243]
	v_add_u32_e32 v175, 0x6000, v182
	v_add_u32_e32 v174, 0x6400, v182
	v_mfma_f32_16x16x32_bf16 v[76:79], v[192:195], v[132:135], v[244:247]
	s_and_saveexec_b64 s[0:1], vcc
	s_cbranch_execz .LBB0_215
	ds_write2_b32 v182, v88, v96 offset1:16
	ds_write2_b32 v182, v89, v97 offset0:128 offset1:144
	ds_write2_b32 v183, v90, v98 offset1:16
	ds_write2_b32 v183, v91, v99 offset0:128 offset1:144
	ds_write2_b32 v182, v80, v84 offset0:32 offset1:48
	ds_write2_b32 v182, v81, v85 offset0:160 offset1:176
	ds_write2_b32 v183, v82, v86 offset0:32 offset1:48
	ds_write2_b32 v183, v83, v87 offset0:160 offset1:176
	ds_write2_b32 v182, v120, v124 offset0:64 offset1:80
	ds_write2_b32 v182, v121, v125 offset0:192 offset1:208
	ds_write2_b32 v183, v122, v126 offset0:64 offset1:80
	ds_write2_b32 v183, v123, v127 offset0:192 offset1:208
	ds_write2_b32 v182, v112, v116 offset0:96 offset1:112
	ds_write2_b32 v182, v113, v117 offset0:224 offset1:240
	ds_write2_b32 v183, v114, v118 offset0:96 offset1:112
	ds_write2_b32 v183, v115, v119 offset0:224 offset1:240
	ds_write2_b32 v181, v40, v52 offset1:16
	ds_write2_b32 v181, v41, v53 offset0:128 offset1:144
	ds_write2_b32 v180, v42, v54 offset1:16
	ds_write2_b32 v180, v43, v55 offset0:128 offset1:144
	ds_write2_b32 v181, v32, v36 offset0:32 offset1:48
	ds_write2_b32 v181, v33, v37 offset0:160 offset1:176
	ds_write2_b32 v180, v34, v38 offset0:32 offset1:48
	ds_write2_b32 v180, v35, v39 offset0:160 offset1:176
	ds_write2_b32 v181, v104, v108 offset0:64 offset1:80
	ds_write2_b32 v181, v105, v109 offset0:192 offset1:208
	ds_write2_b32 v180, v106, v110 offset0:64 offset1:80
	ds_write2_b32 v180, v107, v111 offset0:192 offset1:208
	ds_write2_b32 v181, v92, v100 offset0:96 offset1:112
	ds_write2_b32 v181, v93, v101 offset0:224 offset1:240
	ds_write2_b32 v180, v94, v102 offset0:96 offset1:112
	ds_write2_b32 v180, v95, v103 offset0:224 offset1:240
	ds_write2_b32 v179, v24, v28 offset1:16
	ds_write2_b32 v179, v25, v29 offset0:128 offset1:144
	ds_write2_b32 v178, v26, v30 offset1:16
	ds_write2_b32 v178, v27, v31 offset0:128 offset1:144
	ds_write2_b32 v179, v16, v20 offset0:32 offset1:48
	ds_write2_b32 v179, v17, v21 offset0:160 offset1:176
	ds_write2_b32 v178, v18, v22 offset0:32 offset1:48
	ds_write2_b32 v178, v19, v23 offset0:160 offset1:176
	ds_write2_b32 v179, v56, v60 offset0:64 offset1:80
	ds_write2_b32 v179, v57, v61 offset0:192 offset1:208
	ds_write2_b32 v178, v58, v62 offset0:64 offset1:80
	ds_write2_b32 v178, v59, v63 offset0:192 offset1:208
	ds_write2_b32 v179, v44, v72 offset0:96 offset1:112
	ds_write2_b32 v179, v45, v73 offset0:224 offset1:240
	ds_write2_b32 v178, v46, v74 offset0:96 offset1:112
	ds_write2_b32 v178, v47, v75 offset0:224 offset1:240
	ds_write2_b32 v175, v8, v12 offset1:16
	ds_write2_b32 v175, v9, v13 offset0:128 offset1:144
	ds_write2_b32 v174, v10, v14 offset1:16
	ds_write2_b32 v174, v11, v15 offset0:128 offset1:144
	ds_write2_b32 v175, v0, v4 offset0:32 offset1:48
	ds_write2_b32 v175, v1, v5 offset0:160 offset1:176
	ds_write2_b32 v174, v2, v6 offset0:32 offset1:48
	ds_write2_b32 v174, v3, v7 offset0:160 offset1:176
	ds_write2_b32 v175, v48, v64 offset0:64 offset1:80
	ds_write2_b32 v175, v49, v65 offset0:192 offset1:208
	ds_write2_b32 v174, v50, v66 offset0:64 offset1:80
	ds_write2_b32 v174, v51, v67 offset0:192 offset1:208
	ds_write2_b32 v175, v68, v76 offset0:96 offset1:112
	ds_write2_b32 v175, v69, v77 offset0:224 offset1:240
	ds_write2_b32 v174, v70, v78 offset0:96 offset1:112
	ds_write2_b32 v174, v71, v79 offset0:224 offset1:240

.LBB0_444:
	s_or_b64 exec, exec, s[0:1]
	s_mul_i32 s0, s26, s27
	s_sub_i32 s62, s28, s0
	s_and_b64 s[0:1], vcc, exec
	s_mov_b32 s0, 0x56ba300
	s_cselect_b32 s27, s0, 0x56ba000
	s_add_u32 s0, s14, s27
	s_addc_u32 s1, s15, 0
	s_and_b64 s[6:7], vcc, exec
	s_mov_b32 s6, 0x4d0000
	s_cselect_b32 s63, s6, 0x440000
	s_add_u32 s6, s16, s63
	s_addc_u32 s7, s17, 0
	v_mov_b32_e32 v12, v190
	s_and_b64 s[28:29], vcc, exec
	s_cselect_b32 s29, 0x100, s83
	v_ashrrev_i32_e32 v8, 3, v12
	s_lshl_b32 s28, s62, 8
	v_lshrrev_b32_e32 v13, 4, v12
	v_add_u32_e32 v15, s59, v8
	v_xor_b32_e32 v14, v13, v12
	v_add_u32_e32 v16, 64, v15
	v_mov_b64_e32 v[0:1], s[0:1]
	v_add_u32_e32 v17, 0x80, v15
	v_add_u32_e32 v18, 0xc0, v15
	v_add_u32_e32 v8, s28, v8
	v_mad_i64_i32 v[2:3], s[0:1], v16, s80, v[0:1]
	v_mad_i64_i32 v[4:5], s[0:1], v17, s80, v[0:1]
	v_mad_i64_i32 v[6:7], s[0:1], v18, s80, v[0:1]
	v_mad_i64_i32 v[10:11], s[0:1], v8, s29, 0
	v_mad_i64_i32 v[0:1], s[0:1], v15, s80, v[0:1]
	v_lshlrev_b32_e32 v14, 4, v14
	v_lshl_add_u32 v170, v12, 4, 0
	v_and_b32_e32 v176, 0x70, v14
	v_readfirstlane_b32 s0, v170
	v_lshl_add_u64 v[0:1], v[0:1], 0, v[176:177]
	s_mov_b32 m0, s0
	v_lshl_add_u64 v[2:3], v[2:3], 0, v[176:177]
	global_load_lds_dwordx4 v[0:1], off
	v_add_u32_e32 v0, 0x2000, v170
	v_lshl_add_u64 v[4:5], v[4:5], 0, v[176:177]
	v_readfirstlane_b32 s0, v0
	v_add_u32_e32 v0, 0x4000, v170
	s_mov_b32 m0, s0
	v_readfirstlane_b32 s0, v0
	v_add_u32_e32 v0, 0x6000, v170
	global_load_lds_dwordx4 v[2:3], off
	s_mov_b32 m0, s0
	v_readfirstlane_b32 s0, v0
	v_add_u32_e32 v0, 0x8000, v170
	v_lshl_add_u64 v[10:11], v[10:11], 1, s[6:7]
	v_lshl_add_u64 v[6:7], v[6:7], 0, v[176:177]
	global_load_lds_dwordx4 v[4:5], off
	s_mov_b32 m0, s0
	v_readfirstlane_b32 s0, v0
	v_add_u32_e32 v2, 0xa000, v170
	v_lshl_add_u64 v[10:11], v[10:11], 0, v[176:177]
	global_load_lds_dwordx4 v[6:7], off
	s_mov_b32 m0, s0
	s_lshl_b32 s54, s29, 7
	v_readfirstlane_b32 s0, v2
	v_add_u32_e32 v2, 0xc000, v170
	global_load_lds_dwordx4 v[10:11], off
	v_lshl_add_u64 v[0:1], v[10:11], 0, s[54:55]
	s_mov_b32 m0, s0
	v_readfirstlane_b32 s0, v2
	v_add_u32_e32 v2, 0xe000, v170
	global_load_lds_dwordx4 v[0:1], off
	v_lshl_add_u64 v[0:1], v[0:1], 0, s[54:55]
	s_mov_b32 m0, s0
	v_readfirstlane_b32 s0, v2
	global_load_lds_dwordx4 v[0:1], off
	v_lshl_add_u64 v[0:1], v[0:1], 0, s[54:55]
	s_mov_b32 m0, s0
	s_lshl_b32 s0, s29, 10
	global_load_lds_dwordx4 v[0:1], off
	v_ashrrev_i32_e32 v9, 31, v8
	v_bitop3_b32 v0, v13, 7, v12 bitop3:0x48
	s_add_u32 s6, s41, s63
	v_lshlrev_b32_e32 v176, 4, v0
	v_lshlrev_b64 v[0:1], 1, v[8:9]
	s_addc_u32 s7, s58, 0
	v_lshl_add_u64 v[2:3], v[0:1], 0, s[72:73]
	v_mov_b64_e32 v[4:5], s[6:7]
	v_mad_u64_u32 v[128:129], s[6:7], v2, s29, v[4:5]
	v_mad_i32_i24 v129, v3, s29, v129
	v_lshl_add_u64 v[2:3], v[0:1], 0, s[70:71]
	v_lshrrev_b32_e32 v152, 5, v12
	v_lshrrev_b32_e32 v14, 1, v12
	v_mad_u64_u32 v[130:131], s[6:7], v2, s29, v[4:5]
	v_and_b32_e32 v150, 31, v12
	v_xor_b32_e32 v14, v152, v14
	v_mad_i32_i24 v131, v3, s29, v131
	v_lshl_add_u64 v[2:3], v[0:1], 0, s[66:67]
	v_lshlrev_b32_e32 v19, 7, v150
	v_lshlrev_b32_e32 v14, 4, v14
	v_mad_u64_u32 v[132:133], s[6:7], v2, s29, v[4:5]
	v_mad_u64_u32 v[134:135], s[6:7], v0, s29, v[4:5]
	v_and_or_b32 v14, v14, 16, v19
	v_lshlrev_b32_e32 v19, 3, v12
	s_add_u32 s6, s31, s27
	v_and_b32_e32 v20, 0x60, v19
	v_alignbit_b32 v1, v9, v8, 31
	s_addc_u32 s7, s40, 0
	v_or_b32_e32 v157, v14, v20
	v_bitop3_b32 v156, v14, 32, v20 bitop3:0x36
	v_bitop3_b32 v155, v14, 64, v20 bitop3:0x36
	v_bitop3_b32 v154, v14, s81, v19 bitop3:0x34
	v_ashrrev_i32_e32 v14, 1, v12
	v_mad_i32_i24 v135, v1, s29, v135
	v_mov_b64_e32 v[0:1], s[6:7]
	v_bfe_u32 v151, v12, 7, 1
	v_and_b32_e32 v153, 0xffffff80, v14
	v_and_or_b32 v153, v12, 64, v153
	v_mad_i64_i32 v[142:143], s[6:7], v18, s80, v[0:1]
	v_mad_i64_i32 v[144:145], s[6:7], v17, s80, v[0:1]
	v_mad_i64_i32 v[146:147], s[6:7], v16, s80, v[0:1]
	v_mad_i64_i32 v[148:149], s[6:7], v15, s80, v[0:1]
	v_mov_b32_e32 v0, 0
	v_lshlrev_b32_e32 v169, 7, v153
	v_lshlrev_b32_e32 v168, 14, v151
	v_mad_i32_i24 v133, v3, s29, v133
	s_mov_b32 s1, 0x10000
	v_mov_b32_e32 v1, v0
	v_mov_b32_e32 v2, v0
	v_mov_b32_e32 v3, v0
	v_mov_b32_e32 v4, v0
	v_mov_b32_e32 v5, v0
	v_mov_b32_e32 v6, v0
	v_mov_b32_e32 v7, v0
	v_mov_b32_e32 v8, v0
	v_mov_b32_e32 v9, v0
	v_mov_b32_e32 v10, v0
	v_mov_b32_e32 v11, v0
	v_mov_b32_e32 v12, v0
	v_mov_b32_e32 v13, v0
	v_mov_b32_e32 v14, v0
	v_mov_b32_e32 v15, v0
	v_mov_b32_e32 v16, v0
	v_mov_b32_e32 v17, v0
	v_mov_b32_e32 v18, v0
	v_mov_b32_e32 v19, v0
	v_mov_b32_e32 v20, v0
	v_mov_b32_e32 v21, v0
	v_mov_b32_e32 v22, v0
	v_mov_b32_e32 v23, v0
	v_mov_b32_e32 v24, v0
	v_mov_b32_e32 v25, v0
	v_mov_b32_e32 v26, v0
	v_mov_b32_e32 v27, v0
	v_mov_b32_e32 v28, v0
	v_mov_b32_e32 v29, v0
	v_mov_b32_e32 v30, v0
	v_mov_b32_e32 v31, v0
	v_mov_b32_e32 v32, v0
	v_mov_b32_e32 v33, v0
	v_mov_b32_e32 v34, v0
	v_mov_b32_e32 v35, v0
	v_mov_b32_e32 v36, v0
	v_mov_b32_e32 v37, v0
	v_mov_b32_e32 v38, v0
	v_mov_b32_e32 v39, v0
	v_mov_b32_e32 v40, v0
	v_mov_b32_e32 v41, v0
	v_mov_b32_e32 v42, v0
	v_mov_b32_e32 v43, v0
	v_mov_b32_e32 v44, v0
	v_mov_b32_e32 v45, v0
	v_mov_b32_e32 v46, v0
	v_mov_b32_e32 v47, v0
	v_mov_b32_e32 v48, v0
	v_mov_b32_e32 v49, v0
	v_mov_b32_e32 v50, v0
	v_mov_b32_e32 v51, v0
	v_mov_b32_e32 v52, v0
	v_mov_b32_e32 v53, v0
	v_mov_b32_e32 v54, v0
	v_mov_b32_e32 v55, v0
	v_mov_b32_e32 v56, v0
	v_mov_b32_e32 v57, v0
	v_mov_b32_e32 v58, v0
	v_mov_b32_e32 v59, v0
	v_mov_b32_e32 v60, v0
	v_mov_b32_e32 v61, v0
	v_mov_b32_e32 v62, v0
	v_mov_b32_e32 v63, v0
	v_mov_b32_e32 v64, v0
	v_mov_b32_e32 v65, v0
	v_mov_b32_e32 v66, v0
	v_mov_b32_e32 v67, v0
	v_mov_b32_e32 v68, v0
	v_mov_b32_e32 v69, v0
	v_mov_b32_e32 v70, v0
	v_mov_b32_e32 v71, v0
	v_mov_b32_e32 v72, v0
	v_mov_b32_e32 v73, v0
	v_mov_b32_e32 v74, v0
	v_mov_b32_e32 v75, v0
	v_mov_b32_e32 v76, v0
	v_mov_b32_e32 v77, v0
	v_mov_b32_e32 v78, v0
	v_mov_b32_e32 v79, v0
	v_mov_b32_e32 v80, v0
	v_mov_b32_e32 v81, v0
	v_mov_b32_e32 v82, v0
	v_mov_b32_e32 v83, v0
	v_mov_b32_e32 v84, v0
	v_mov_b32_e32 v85, v0
	v_mov_b32_e32 v86, v0
	v_mov_b32_e32 v87, v0
	v_mov_b32_e32 v88, v0
	v_mov_b32_e32 v89, v0
	v_mov_b32_e32 v90, v0
	v_mov_b32_e32 v91, v0
	v_mov_b32_e32 v92, v0
	v_mov_b32_e32 v93, v0
	v_mov_b32_e32 v94, v0
	v_mov_b32_e32 v95, v0
	v_mov_b32_e32 v96, v0
	v_mov_b32_e32 v97, v0
	v_mov_b32_e32 v98, v0
	v_mov_b32_e32 v99, v0
	v_mov_b32_e32 v100, v0
	v_mov_b32_e32 v101, v0
	v_mov_b32_e32 v102, v0
	v_mov_b32_e32 v103, v0
	v_mov_b32_e32 v104, v0
	v_mov_b32_e32 v105, v0
	v_mov_b32_e32 v106, v0
	v_mov_b32_e32 v107, v0
	v_mov_b32_e32 v108, v0
	v_mov_b32_e32 v109, v0
	v_mov_b32_e32 v110, v0
	v_mov_b32_e32 v111, v0
	v_mov_b32_e32 v112, v0
	v_mov_b32_e32 v113, v0
	v_mov_b32_e32 v114, v0
	v_mov_b32_e32 v115, v0
	v_mov_b32_e32 v116, v0
	v_mov_b32_e32 v117, v0
	v_mov_b32_e32 v118, v0
	v_mov_b32_e32 v119, v0
	v_mov_b32_e32 v120, v0
	v_mov_b32_e32 v121, v0
	v_mov_b32_e32 v122, v0
	v_mov_b32_e32 v123, v0
	v_mov_b32_e32 v124, v0
	v_mov_b32_e32 v125, v0
	v_mov_b32_e32 v126, v0
	v_mov_b32_e32 v127, v0

.LBB0_658:
	s_ashr_i32 s2, s0, 7
	s_mul_i32 s1, s2, 33
	s_bfe_u32 s3, s0, 0x50002
	s_add_i32 s10, s1, s3
	s_add_i32 s10, s10, 1
	v_mov_b32_e32 v14, v190
	s_lshl_b32 s17, s10, 8
	s_lshl_b32 s0, s0, 8
	s_and_b32 s12, s0, 0x300
	v_ashrrev_i32_e32 v15, 3, v14
	v_lshrrev_b32_e32 v16, 4, v14
	v_add_u32_e32 v18, s17, v15
	v_xor_b32_e32 v17, v16, v14
	v_add_u32_e32 v2, 64, v18
	v_mov_b64_e32 v[0:1], s[42:43]
	v_add_u32_e32 v4, 0x80, v18
	v_add_u32_e32 v6, 0xc0, v18
	v_add_u32_e32 v12, s12, v15
	v_mov_b64_e32 v[10:11], s[58:59]
	v_mad_i64_i32 v[2:3], s[0:1], v2, s78, v[0:1]
	v_mad_i64_i32 v[4:5], s[0:1], v4, s78, v[0:1]
	v_mad_i64_i32 v[6:7], s[0:1], v6, s78, v[0:1]
	v_mad_i64_i32 v[8:9], s[0:1], v12, s78, 0
	v_mad_i64_i32 v[10:11], s[0:1], v12, s78, v[10:11]
	v_mad_i64_i32 v[12:13], s[0:1], v18, s78, 0
	v_mad_i64_i32 v[0:1], s[0:1], v18, s78, v[0:1]
	v_lshlrev_b32_e32 v17, 4, v17
	v_lshl_add_u32 v150, v14, 4, 0
	v_and_b32_e32 v176, 0x70, v17
	v_readfirstlane_b32 s0, v150
	v_lshl_add_u64 v[0:1], v[0:1], 0, v[176:177]
	s_mov_b32 m0, s0
	v_lshl_add_u64 v[2:3], v[2:3], 0, v[176:177]
	global_load_lds_dwordx4 v[0:1], off
	v_add_u32_e32 v0, 0x2000, v150
	v_lshl_add_u64 v[4:5], v[4:5], 0, v[176:177]
	v_readfirstlane_b32 s0, v0
	v_add_u32_e32 v0, 0x4000, v150
	s_mov_b32 m0, s0
	v_readfirstlane_b32 s0, v0
	v_add_u32_e32 v0, 0x6000, v150
	global_load_lds_dwordx4 v[2:3], off
	s_mov_b32 m0, s0
	v_readfirstlane_b32 s0, v0
	v_add_u32_e32 v0, 0x8000, v150
	v_lshl_add_u64 v[6:7], v[6:7], 0, v[176:177]
	global_load_lds_dwordx4 v[4:5], off
	s_mov_b32 m0, s0
	v_readfirstlane_b32 s0, v0
	v_lshl_add_u64 v[10:11], v[10:11], 0, v[176:177]
	global_load_lds_dwordx4 v[6:7], off
	s_mov_b32 m0, s0
	s_mov_b64 s[0:1], 0x22000
	v_add_u32_e32 v2, 0xa000, v150
	v_lshl_add_u64 v[0:1], v[10:11], 0, s[0:1]
	v_readfirstlane_b32 s0, v2
	global_load_lds_dwordx4 v[10:11], off
	s_mov_b32 m0, s0
	s_mov_b64 s[0:1], 0x44000
	v_add_u32_e32 v2, 0xc000, v150
	global_load_lds_dwordx4 v[0:1], off
	v_lshl_add_u64 v[0:1], v[10:11], 0, s[0:1]
	v_readfirstlane_b32 s0, v2
	s_mov_b32 m0, s0
	s_mov_b64 s[0:1], 0x66000
	v_add_u32_e32 v2, 0xe000, v150
	global_load_lds_dwordx4 v[0:1], off
	v_lshl_add_u64 v[0:1], v[10:11], 0, s[0:1]
	v_readfirstlane_b32 s0, v2
	s_mov_b32 m0, s0
	s_mulk_i32 s2, 0x2100
	global_load_lds_dwordx4 v[0:1], off
	s_lshl_b32 s13, s3, 8
	s_add_i32 s13, s13, s2
	v_bitop3_b32 v0, v16, 7, v14 bitop3:0x48
	v_add_u32_e32 v3, s13, v15
	v_lshlrev_b32_e32 v2, 4, v0
	v_add_u32_e32 v0, 0x140, v3
	v_mad_i64_i32 v[0:1], s[0:1], v0, s78, 0
	v_or_b32_e32 v0, v0, v2
	v_lshl_add_u64 v[130:131], s[48:49], 0, v[0:1]
	v_add_u32_e32 v0, 0x180, v3
	v_mad_i64_i32 v[0:1], s[0:1], v0, s78, 0
	v_and_b32_e32 v139, 15, v14
	v_bfe_u32 v140, v14, 4, 2
	v_bfe_u32 v17, v14, 1, 3
	v_or_b32_e32 v0, v0, v2
	v_lshlrev_b32_e32 v18, 7, v139
	v_bitop3_b32 v19, v16, v17, 3 bitop3:0x6c
	v_bitop3_b32 v17, v140, v17, 4 bitop3:0x36
	v_lshl_add_u64 v[132:133], s[48:49], 0, v[0:1]
	v_add_u32_e32 v0, 0x1c0, v3
	v_lshl_or_b32 v146, v17, 4, v18
	v_ashrrev_i32_e32 v17, 1, v14
	v_mad_i64_i32 v[0:1], s[0:1], v0, s78, 0
	v_bfe_u32 v138, v14, 7, 1
	v_and_b32_e32 v141, 0xffffff80, v17
	v_and_or_b32 v141, v14, 64, v141
	v_or_b32_e32 v12, v12, v2
	v_or_b32_e32 v0, v0, v2
	v_or_b32_e32 v8, v8, v2
	v_mov_b32_e32 v108, 0
	v_lshl_or_b32 v147, v19, 4, v18
	v_lshlrev_b32_e32 v149, 7, v141
	v_lshlrev_b32_e32 v148, 14, v138
	v_lshl_add_u64 v[128:129], s[48:49], 0, v[12:13]
	v_lshl_add_u64 v[134:135], s[48:49], 0, v[0:1]
	v_lshl_add_u64 v[136:137], s[8:9], 0, v[8:9]
	s_mov_b64 s[2:3], 0
	s_mov_b32 s0, 0
	v_mov_b32_e32 v109, v108
	v_mov_b32_e32 v110, v108
	v_mov_b32_e32 v111, v108
	v_mov_b32_e32 v0, v108
	v_mov_b32_e32 v1, v108
	v_mov_b32_e32 v2, v108
	v_mov_b32_e32 v3, v108
	v_mov_b32_e32 v4, v108
	v_mov_b32_e32 v5, v108
	v_mov_b32_e32 v6, v108
	v_mov_b32_e32 v7, v108
	v_mov_b32_e32 v8, v108
	v_mov_b32_e32 v9, v108
	v_mov_b32_e32 v10, v108
	v_mov_b32_e32 v11, v108
	v_mov_b32_e32 v16, v108
	v_mov_b32_e32 v17, v108
	v_mov_b32_e32 v18, v108
	v_mov_b32_e32 v19, v108
	v_mov_b32_e32 v24, v108
	v_mov_b32_e32 v25, v108
	v_mov_b32_e32 v26, v108
	v_mov_b32_e32 v27, v108
	v_mov_b32_e32 v32, v108
	v_mov_b32_e32 v33, v108
	v_mov_b32_e32 v34, v108
	v_mov_b32_e32 v35, v108
	v_mov_b32_e32 v40, v108
	v_mov_b32_e32 v41, v108
	v_mov_b32_e32 v42, v108
	v_mov_b32_e32 v43, v108
	v_mov_b32_e32 v12, v108
	v_mov_b32_e32 v13, v108
	v_mov_b32_e32 v14, v108
	v_mov_b32_e32 v15, v108
	v_mov_b32_e32 v20, v108
	v_mov_b32_e32 v21, v108
	v_mov_b32_e32 v22, v108
	v_mov_b32_e32 v23, v108
	v_mov_b32_e32 v28, v108
	v_mov_b32_e32 v29, v108
	v_mov_b32_e32 v30, v108
	v_mov_b32_e32 v31, v108
	v_mov_b32_e32 v36, v108
	v_mov_b32_e32 v37, v108
	v_mov_b32_e32 v38, v108
	v_mov_b32_e32 v39, v108
	v_mov_b32_e32 v48, v108
	v_mov_b32_e32 v49, v108
	v_mov_b32_e32 v50, v108
	v_mov_b32_e32 v51, v108
	v_mov_b32_e32 v56, v108
	v_mov_b32_e32 v57, v108
	v_mov_b32_e32 v58, v108
	v_mov_b32_e32 v59, v108
	v_mov_b32_e32 v64, v108
	v_mov_b32_e32 v65, v108
	v_mov_b32_e32 v66, v108
	v_mov_b32_e32 v67, v108
	v_mov_b32_e32 v72, v108
	v_mov_b32_e32 v73, v108
	v_mov_b32_e32 v74, v108
	v_mov_b32_e32 v75, v108
	v_mov_b32_e32 v44, v108
	v_mov_b32_e32 v45, v108
	v_mov_b32_e32 v46, v108
	v_mov_b32_e32 v47, v108
	v_mov_b32_e32 v52, v108
	v_mov_b32_e32 v53, v108
	v_mov_b32_e32 v54, v108
	v_mov_b32_e32 v55, v108
	v_mov_b32_e32 v60, v108
	v_mov_b32_e32 v61, v108
	v_mov_b32_e32 v62, v108
	v_mov_b32_e32 v63, v108
	v_mov_b32_e32 v68, v108
	v_mov_b32_e32 v69, v108
	v_mov_b32_e32 v70, v108
	v_mov_b32_e32 v71, v108
	v_mov_b32_e32 v80, v108
	v_mov_b32_e32 v81, v108
	v_mov_b32_e32 v82, v108
	v_mov_b32_e32 v83, v108
	v_mov_b32_e32 v88, v108
	v_mov_b32_e32 v89, v108
	v_mov_b32_e32 v90, v108
	v_mov_b32_e32 v91, v108
	v_mov_b32_e32 v96, v108
	v_mov_b32_e32 v97, v108
	v_mov_b32_e32 v98, v108
	v_mov_b32_e32 v99, v108
	v_mov_b32_e32 v104, v108
	v_mov_b32_e32 v105, v108
	v_mov_b32_e32 v106, v108
	v_mov_b32_e32 v107, v108
	v_mov_b32_e32 v76, v108
	v_mov_b32_e32 v77, v108
	v_mov_b32_e32 v78, v108
	v_mov_b32_e32 v79, v108
	v_mov_b32_e32 v84, v108
	v_mov_b32_e32 v85, v108
	v_mov_b32_e32 v86, v108
	v_mov_b32_e32 v87, v108
	v_mov_b32_e32 v92, v108
	v_mov_b32_e32 v93, v108
	v_mov_b32_e32 v94, v108
	v_mov_b32_e32 v95, v108
	v_mov_b32_e32 v100, v108
	v_mov_b32_e32 v101, v108
	v_mov_b32_e32 v102, v108
	v_mov_b32_e32 v103, v108
	v_mov_b32_e32 v112, v108
	v_mov_b32_e32 v113, v108
	v_mov_b32_e32 v114, v108
	v_mov_b32_e32 v115, v108
	v_mov_b32_e32 v116, v108
	v_mov_b32_e32 v117, v108
	v_mov_b32_e32 v118, v108
	v_mov_b32_e32 v119, v108
	v_mov_b32_e32 v120, v108
	v_mov_b32_e32 v121, v108
	v_mov_b32_e32 v122, v108
	v_mov_b32_e32 v123, v108
	v_mov_b32_e32 v124, v108
	v_mov_b32_e32 v125, v108
	v_mov_b32_e32 v126, v108
	v_mov_b32_e32 v127, v108
.LBB0_659:
	s_add_i32 s1, s0, 0x10000
	s_and_b32 s11, s1, 0x10000
	s_waitcnt vmcnt(0)
	s_barrier
	s_and_b32 s0, s0, 0x10000
	s_add_i32 s0, s0, 0
	v_add_u32_e32 v151, s0, v149
	v_add_u32_e32 v164, v151, v147
	ds_read_b128 v[152:155], v164
	ds_read_b128 v[156:159], v164 offset:2048
	ds_read_b128 v[160:163], v164 offset:4096
	ds_read_b128 v[164:167], v164 offset:6144
	v_add_u32_e32 v251, v151, v146
	v_add_u32_e32 v176, s0, v148
	v_add_u32_e32 v186, v176, v147
	ds_read_b128 v[168:171], v186 offset:32768
	ds_read_b128 v[172:175], v186 offset:34816
	ds_read_b128 v[178:181], v186 offset:36864
	ds_read_b128 v[182:185], v186 offset:38912
	v_add_u32_e32 v250, v176, v146
	ds_read_b128 v[212:215], v186 offset:40960
	ds_read_b128 v[216:219], v186 offset:43008
	ds_read_b128 v[220:223], v186 offset:45056
	ds_read_b128 v[224:227], v186 offset:47104
	v_add_u32_e32 v254, s11, v150
	v_add_u32_e32 v228, 0x2000, v254
	v_readfirstlane_b32 s11, v254
	v_lshl_add_u64 v[188:189], v[128:129], 0, s[2:3]
	s_mov_b32 m0, s11
	v_readfirstlane_b32 s11, v228
	v_add_u32_e32 v228, 0x4000, v254
	global_load_lds_dwordx4 v[188:189], off
	v_lshl_add_u64 v[188:189], v[130:131], 0, s[2:3]
	s_mov_b32 m0, s11
	s_waitcnt lgkmcnt(4)
	v_mfma_f32_16x16x32_bf16 v[124:127], v[152:155], v[168:171], v[124:127]
	ds_read_b128 v[192:195], v251
	v_mfma_f32_16x16x32_bf16 v[120:123], v[152:155], v[172:175], v[120:123]
	ds_read_b128 v[198:201], v251 offset:2048
	v_readfirstlane_b32 s11, v228
	v_add_u32_e32 v228, 0x6000, v254
	global_load_lds_dwordx4 v[188:189], off
	v_mfma_f32_16x16x32_bf16 v[116:119], v[152:155], v[178:181], v[116:119]
	ds_read_b128 v[204:207], v251 offset:4096
	v_lshl_add_u64 v[188:189], v[132:133], 0, s[2:3]
	s_mov_b32 m0, s11
	v_readfirstlane_b32 s11, v228
	v_mfma_f32_16x16x32_bf16 v[112:115], v[152:155], v[182:185], v[112:115]
	ds_read_b128 v[208:211], v251 offset:6144
	global_load_lds_dwordx4 v[188:189], off
	v_lshl_add_u64 v[188:189], v[134:135], 0, s[2:3]
	s_mov_b32 m0, s11
	v_mfma_f32_16x16x32_bf16 v[104:107], v[156:159], v[168:171], v[104:107]
	v_add_u32_e32 v253, 0x8000, v254
	global_load_lds_dwordx4 v[188:189], off
	v_lshl_add_u64 v[188:189], v[136:137], 0, s[2:3]
	v_mfma_f32_16x16x32_bf16 v[96:99], v[156:159], v[172:175], v[96:99]
	s_mov_b64 s[18:19], 0x550080
	v_readfirstlane_b32 s11, v253
	v_add_u32_e32 v253, 0xa000, v254
	v_mfma_f32_16x16x32_bf16 v[88:91], v[156:159], v[178:181], v[88:91]
	v_lshl_add_u64 v[228:229], v[188:189], 0, s[18:19]
	s_mov_b32 m0, s11
	s_mov_b64 s[18:19], 0x572080
	v_mfma_f32_16x16x32_bf16 v[80:83], v[156:159], v[182:185], v[80:83]
	v_readfirstlane_b32 s11, v253
	v_add_u32_e32 v253, 0xc000, v254
	global_load_lds_dwordx4 v[228:229], off
	v_mfma_f32_16x16x32_bf16 v[72:75], v[160:163], v[168:171], v[72:75]
	v_lshl_add_u64 v[228:229], v[188:189], 0, s[18:19]
	s_mov_b32 m0, s11
	s_mov_b64 s[18:19], 0x594080
	v_mfma_f32_16x16x32_bf16 v[64:67], v[160:163], v[172:175], v[64:67]
	v_readfirstlane_b32 s11, v253
	v_add_u32_e32 v254, 0xe000, v254
	global_load_lds_dwordx4 v[228:229], off
	v_mfma_f32_16x16x32_bf16 v[56:59], v[160:163], v[178:181], v[56:59]
	v_lshl_add_u64 v[228:229], v[188:189], 0, s[18:19]
	s_mov_b32 m0, s11
	s_mov_b64 s[18:19], 0x5b6080
	v_mfma_f32_16x16x32_bf16 v[48:51], v[160:163], v[182:185], v[48:51]
	v_readfirstlane_b32 s11, v254
	global_load_lds_dwordx4 v[228:229], off
	v_lshl_add_u64 v[188:189], v[188:189], 0, s[18:19]
	v_mfma_f32_16x16x32_bf16 v[40:43], v[164:167], v[168:171], v[40:43]
	s_mov_b32 m0, s11
	global_load_lds_dwordx4 v[188:189], off
	v_mfma_f32_16x16x32_bf16 v[32:35], v[164:167], v[172:175], v[32:35]
	v_mfma_f32_16x16x32_bf16 v[24:27], v[164:167], v[178:181], v[24:27]
	v_mfma_f32_16x16x32_bf16 v[16:19], v[164:167], v[182:185], v[16:19]
	s_waitcnt lgkmcnt(4)
	v_mfma_f32_16x16x32_bf16 v[100:103], v[152:155], v[212:215], v[100:103]
	v_mfma_f32_16x16x32_bf16 v[92:95], v[152:155], v[216:219], v[92:95]
	v_mfma_f32_16x16x32_bf16 v[84:87], v[152:155], v[220:223], v[84:87]
	ds_read_b128 v[168:171], v250 offset:32768
	v_mfma_f32_16x16x32_bf16 v[76:79], v[152:155], v[224:227], v[76:79]
	ds_read_b128 v[172:175], v250 offset:34816
	v_mfma_f32_16x16x32_bf16 v[68:71], v[156:159], v[212:215], v[68:71]
	ds_read_b128 v[178:181], v250 offset:36864
	v_mfma_f32_16x16x32_bf16 v[60:63], v[156:159], v[216:219], v[60:63]
	ds_read_b128 v[182:185], v250 offset:38912
	v_mfma_f32_16x16x32_bf16 v[52:55], v[156:159], v[220:223], v[52:55]
	v_mfma_f32_16x16x32_bf16 v[44:47], v[156:159], v[224:227], v[44:47]
	v_mfma_f32_16x16x32_bf16 v[36:39], v[160:163], v[212:215], v[36:39]
	v_mfma_f32_16x16x32_bf16 v[28:31], v[160:163], v[216:219], v[28:31]
	v_mfma_f32_16x16x32_bf16 v[20:23], v[160:163], v[220:223], v[20:23]
	v_mfma_f32_16x16x32_bf16 v[12:15], v[160:163], v[224:227], v[12:15]
	v_mfma_f32_16x16x32_bf16 v[8:11], v[164:167], v[212:215], v[8:11]
	v_mfma_f32_16x16x32_bf16 v[4:7], v[164:167], v[216:219], v[4:7]
	v_mfma_f32_16x16x32_bf16 v[0:3], v[164:167], v[220:223], v[0:3]
	v_mfma_f32_16x16x32_bf16 v[108:111], v[164:167], v[224:227], v[108:111]
	s_waitcnt lgkmcnt(0)
	v_mfma_f32_16x16x32_bf16 v[124:127], v[192:195], v[168:171], v[124:127]
	ds_read_b128 v[212:215], v250 offset:40960
	v_mfma_f32_16x16x32_bf16 v[120:123], v[192:195], v[172:175], v[120:123]
	ds_read_b128 v[216:219], v250 offset:43008
	v_mfma_f32_16x16x32_bf16 v[116:119], v[192:195], v[178:181], v[116:119]
	ds_read_b128 v[220:223], v250 offset:45056
	v_mfma_f32_16x16x32_bf16 v[112:115], v[192:195], v[182:185], v[112:115]
	ds_read_b128 v[224:227], v250 offset:47104
	v_mfma_f32_16x16x32_bf16 v[104:107], v[198:201], v[168:171], v[104:107]
	v_mfma_f32_16x16x32_bf16 v[96:99], v[198:201], v[172:175], v[96:99]
	v_mfma_f32_16x16x32_bf16 v[88:91], v[198:201], v[178:181], v[88:91]
	v_mfma_f32_16x16x32_bf16 v[80:83], v[198:201], v[182:185], v[80:83]
	v_mfma_f32_16x16x32_bf16 v[72:75], v[204:207], v[168:171], v[72:75]
	v_mfma_f32_16x16x32_bf16 v[64:67], v[204:207], v[172:175], v[64:67]
	v_mfma_f32_16x16x32_bf16 v[56:59], v[204:207], v[178:181], v[56:59]
	v_mfma_f32_16x16x32_bf16 v[48:51], v[204:207], v[182:185], v[48:51]
	v_mfma_f32_16x16x32_bf16 v[40:43], v[208:211], v[168:171], v[40:43]
	v_mfma_f32_16x16x32_bf16 v[32:35], v[208:211], v[172:175], v[32:35]
	v_mfma_f32_16x16x32_bf16 v[24:27], v[208:211], v[178:181], v[24:27]
	v_mfma_f32_16x16x32_bf16 v[16:19], v[208:211], v[182:185], v[16:19]
	s_waitcnt lgkmcnt(0)
	v_mfma_f32_16x16x32_bf16 v[100:103], v[192:195], v[212:215], v[100:103]
	v_mfma_f32_16x16x32_bf16 v[92:95], v[192:195], v[216:219], v[92:95]
	v_mfma_f32_16x16x32_bf16 v[84:87], v[192:195], v[220:223], v[84:87]
	v_mfma_f32_16x16x32_bf16 v[76:79], v[192:195], v[224:227], v[76:79]
	v_mfma_f32_16x16x32_bf16 v[68:71], v[198:201], v[212:215], v[68:71]
	v_mfma_f32_16x16x32_bf16 v[60:63], v[198:201], v[216:219], v[60:63]
	v_mfma_f32_16x16x32_bf16 v[52:55], v[198:201], v[220:223], v[52:55]
	v_mfma_f32_16x16x32_bf16 v[44:47], v[198:201], v[224:227], v[44:47]
	v_mfma_f32_16x16x32_bf16 v[36:39], v[204:207], v[212:215], v[36:39]
	v_mfma_f32_16x16x32_bf16 v[28:31], v[204:207], v[216:219], v[28:31]
	v_mfma_f32_16x16x32_bf16 v[20:23], v[204:207], v[220:223], v[20:23]
	v_mfma_f32_16x16x32_bf16 v[12:15], v[204:207], v[224:227], v[12:15]
	s_add_u32 s2, s2, 0x80
	s_addc_u32 s3, s3, 0
	s_cmpk_eq_i32 s2, 0x780
	s_mov_b32 s0, s1
	v_mfma_f32_16x16x32_bf16 v[8:11], v[208:211], v[212:215], v[8:11]
	v_mfma_f32_16x16x32_bf16 v[4:7], v[208:211], v[216:219], v[4:7]
	v_mfma_f32_16x16x32_bf16 v[0:3], v[208:211], v[220:223], v[0:3]
	v_mfma_f32_16x16x32_bf16 v[108:111], v[208:211], v[224:227], v[108:111]
	s_cbranch_scc0 .LBB0_659
	s_add_i32 s0, 0, 0x10000
	v_add_u32_e32 v136, s0, v149
	v_add_u32_e32 v137, v136, v147
	s_waitcnt vmcnt(0)
	s_barrier
	ds_read_b128 v[128:131], v137
	ds_read_b128 v[132:135], v137 offset:2048
	ds_read_b128 v[150:153], v137 offset:4096
	ds_read_b128 v[154:157], v137 offset:6144
	v_add_u32_e32 v137, s0, v148
	v_add_u32_e32 v147, v137, v147
	ds_read_b128 v[158:161], v147 offset:32768
	ds_read_b128 v[162:165], v147 offset:34816
	ds_read_b128 v[166:169], v147 offset:36864
	ds_read_b128 v[170:173], v147 offset:38912
	s_waitcnt lgkmcnt(0)
	v_mfma_f32_16x16x32_bf16 v[124:127], v[128:131], v[158:161], v[124:127]
	v_mfma_f32_16x16x32_bf16 v[120:123], v[128:131], v[162:165], v[120:123]
	v_mfma_f32_16x16x32_bf16 v[116:119], v[128:131], v[166:169], v[116:119]
	v_mfma_f32_16x16x32_bf16 v[112:115], v[128:131], v[170:173], v[112:115]
	v_mfma_f32_16x16x32_bf16 v[104:107], v[132:135], v[158:161], v[104:107]
	v_mfma_f32_16x16x32_bf16 v[72:75], v[150:153], v[158:161], v[72:75]
	v_mfma_f32_16x16x32_bf16 v[64:67], v[150:153], v[162:165], v[64:67]
	v_mfma_f32_16x16x32_bf16 v[56:59], v[150:153], v[166:169], v[56:59]
	v_mfma_f32_16x16x32_bf16 v[48:51], v[150:153], v[170:173], v[48:51]
	v_mfma_f32_16x16x32_bf16 v[178:181], v[132:135], v[162:165], v[96:99]
	v_mfma_f32_16x16x32_bf16 v[182:185], v[132:135], v[166:169], v[88:91]
	v_mfma_f32_16x16x32_bf16 v[186:189], v[132:135], v[170:173], v[80:83]
	v_mfma_f32_16x16x32_bf16 v[158:161], v[154:157], v[158:161], v[40:43]
	v_mfma_f32_16x16x32_bf16 v[162:165], v[154:157], v[162:165], v[32:35]
	v_mfma_f32_16x16x32_bf16 v[166:169], v[154:157], v[166:169], v[24:27]
	v_mfma_f32_16x16x32_bf16 v[170:173], v[154:157], v[170:173], v[16:19]
	s_nop 2
	ds_read_b128 v[16:19], v147 offset:40960
	ds_read_b128 v[24:27], v147 offset:43008
	ds_read_b128 v[32:35], v147 offset:45056
	ds_read_b128 v[40:43], v147 offset:47104
	s_waitcnt lgkmcnt(0)
	v_mfma_f32_16x16x32_bf16 v[100:103], v[128:131], v[16:19], v[100:103]
	v_mfma_f32_16x16x32_bf16 v[92:95], v[128:131], v[24:27], v[92:95]
	v_mfma_f32_16x16x32_bf16 v[192:195], v[128:131], v[32:35], v[84:87]
	v_mfma_f32_16x16x32_bf16 v[76:79], v[128:131], v[40:43], v[76:79]
	v_mfma_f32_16x16x32_bf16 v[68:71], v[132:135], v[16:19], v[68:71]
	v_mfma_f32_16x16x32_bf16 v[60:63], v[132:135], v[24:27], v[60:63]
	v_mfma_f32_16x16x32_bf16 v[128:131], v[132:135], v[32:35], v[52:55]
	v_mfma_f32_16x16x32_bf16 v[44:47], v[132:135], v[40:43], v[44:47]
	v_mfma_f32_16x16x32_bf16 v[132:135], v[150:153], v[16:19], v[36:39]
	v_mfma_f32_16x16x32_bf16 v[198:201], v[150:153], v[24:27], v[28:31]
	v_mfma_f32_16x16x32_bf16 v[204:207], v[150:153], v[32:35], v[20:23]
	v_mfma_f32_16x16x32_bf16 v[148:151], v[150:153], v[40:43], v[12:15]
	v_mfma_f32_16x16x32_bf16 v[208:211], v[154:157], v[16:19], v[8:11]
	v_mfma_f32_16x16x32_bf16 v[212:215], v[154:157], v[24:27], v[4:7]
	v_mfma_f32_16x16x32_bf16 v[216:219], v[154:157], v[32:35], v[0:3]
	v_mfma_f32_16x16x32_bf16 v[154:157], v[154:157], v[40:43], v[108:111]
	s_nop 1
	v_add_u32_e32 v0, v136, v146
	v_add_u32_e32 v136, v137, v146
	ds_read_b128 v[108:111], v0
	ds_read_b128 v[220:223], v0 offset:2048
	ds_read_b128 v[224:227], v0 offset:4096
	ds_read_b128 v[228:231], v0 offset:6144
	ds_read_b128 v[0:3], v136 offset:32768
	ds_read_b128 v[4:7], v136 offset:34816
	ds_read_b128 v[232:235], v136 offset:36864
	ds_read_b128 v[236:239], v136 offset:38912
	s_waitcnt lgkmcnt(0)
	v_mfma_f32_16x16x32_bf16 v[88:91], v[108:111], v[0:3], v[124:127]
	v_mfma_f32_16x16x32_bf16 v[96:99], v[108:111], v[4:7], v[120:123]
	v_mfma_f32_16x16x32_bf16 v[80:83], v[108:111], v[232:235], v[116:119]
	v_mfma_f32_16x16x32_bf16 v[84:87], v[108:111], v[236:239], v[112:115]
	v_mfma_f32_16x16x32_bf16 v[40:43], v[220:223], v[0:3], v[104:107]
	v_mfma_f32_16x16x32_bf16 v[52:55], v[220:223], v[4:7], v[178:181]
	v_mfma_f32_16x16x32_bf16 v[32:35], v[220:223], v[232:235], v[182:185]
	v_mfma_f32_16x16x32_bf16 v[36:39], v[220:223], v[236:239], v[186:189]
	v_mfma_f32_16x16x32_bf16 v[24:27], v[224:227], v[0:3], v[72:75]
	v_mfma_f32_16x16x32_bf16 v[28:31], v[224:227], v[4:7], v[64:67]
	v_mfma_f32_16x16x32_bf16 v[16:19], v[224:227], v[232:235], v[56:59]
	v_mfma_f32_16x16x32_bf16 v[20:23], v[224:227], v[236:239], v[48:51]
	v_mfma_f32_16x16x32_bf16 v[8:11], v[228:231], v[0:3], v[158:161]
	v_mfma_f32_16x16x32_bf16 v[12:15], v[228:231], v[4:7], v[162:165]
	v_mfma_f32_16x16x32_bf16 v[0:3], v[228:231], v[232:235], v[166:169]
	v_mfma_f32_16x16x32_bf16 v[4:7], v[228:231], v[236:239], v[170:173]
	ds_read_b128 v[48:51], v136 offset:40960
	ds_read_b128 v[64:67], v136 offset:43008
	ds_read_b128 v[158:161], v136 offset:45056
	ds_read_b128 v[162:165], v136 offset:47104
	s_waitcnt lgkmcnt(0)
	v_mfma_f32_16x16x32_bf16 v[104:107], v[220:223], v[48:51], v[68:71]
	v_cmp_ne_u32_e32 vcc, 0, v138
	v_cmp_eq_u32_e64 s[2:3], 0, v138
	s_waitcnt vmcnt(0)
	v_lshl_or_b32 v68, v140, 2, v141
	v_lshl_add_u32 v69, v139, 2, 0
	v_mfma_f32_16x16x32_bf16 v[120:123], v[108:111], v[48:51], v[100:103]
	v_lshl_add_u32 v152, v68, 9, v69
	v_add_u32_e32 v153, 0x400, v152
	v_add_u32_e32 v147, 0x6000, v152
	v_mfma_f32_16x16x32_bf16 v[124:127], v[108:111], v[64:67], v[92:95]
	v_add_u32_e32 v146, 0x6400, v152
	s_barrier
	v_mfma_f32_16x16x32_bf16 v[112:115], v[108:111], v[158:161], v[192:195]
	v_mfma_f32_16x16x32_bf16 v[116:119], v[108:111], v[162:165], v[76:79]
	v_mfma_f32_16x16x32_bf16 v[108:111], v[220:223], v[64:67], v[60:63]
	v_mfma_f32_16x16x32_bf16 v[92:95], v[220:223], v[158:161], v[128:131]
	v_mfma_f32_16x16x32_bf16 v[100:103], v[220:223], v[162:165], v[44:47]
	v_mfma_f32_16x16x32_bf16 v[56:59], v[224:227], v[48:51], v[132:135]
	v_mfma_f32_16x16x32_bf16 v[60:63], v[224:227], v[64:67], v[198:201]
	v_mfma_f32_16x16x32_bf16 v[44:47], v[224:227], v[158:161], v[204:207]
	v_mfma_f32_16x16x32_bf16 v[72:75], v[224:227], v[162:165], v[148:151]
	v_mfma_f32_16x16x32_bf16 v[48:51], v[228:231], v[48:51], v[208:211]
	s_nop 1
	v_add_u32_e32 v151, 0x2000, v152
	v_add_u32_e32 v150, 0x2400, v152
	v_add_u32_e32 v149, 0x4000, v152
	v_mfma_f32_16x16x32_bf16 v[64:67], v[228:231], v[64:67], v[212:215]
	v_add_u32_e32 v148, 0x4400, v152
	v_mfma_f32_16x16x32_bf16 v[68:71], v[228:231], v[158:161], v[216:219]
	v_mfma_f32_16x16x32_bf16 v[76:79], v[228:231], v[162:165], v[154:157]
	s_and_saveexec_b64 s[0:1], s[2:3]
	s_cbranch_execz .LBB0_662
	ds_write2_b32 v152, v88, v96 offset1:16
	ds_write2_b32 v152, v89, v97 offset0:128 offset1:144
	ds_write2_b32 v153, v90, v98 offset1:16
	ds_write2_b32 v153, v91, v99 offset0:128 offset1:144
	ds_write2_b32 v152, v80, v84 offset0:32 offset1:48
	ds_write2_b32 v152, v81, v85 offset0:160 offset1:176
	ds_write2_b32 v153, v82, v86 offset0:32 offset1:48
	ds_write2_b32 v153, v83, v87 offset0:160 offset1:176
	ds_write2_b32 v152, v120, v124 offset0:64 offset1:80
	ds_write2_b32 v152, v121, v125 offset0:192 offset1:208
	ds_write2_b32 v153, v122, v126 offset0:64 offset1:80
	ds_write2_b32 v153, v123, v127 offset0:192 offset1:208
	ds_write2_b32 v152, v112, v116 offset0:96 offset1:112
	ds_write2_b32 v152, v113, v117 offset0:224 offset1:240
	ds_write2_b32 v153, v114, v118 offset0:96 offset1:112
	ds_write2_b32 v153, v115, v119 offset0:224 offset1:240
	ds_write2_b32 v151, v40, v52 offset1:16
	ds_write2_b32 v151, v41, v53 offset0:128 offset1:144
	ds_write2_b32 v150, v42, v54 offset1:16
	ds_write2_b32 v150, v43, v55 offset0:128 offset1:144
	ds_write2_b32 v151, v32, v36 offset0:32 offset1:48
	ds_write2_b32 v151, v33, v37 offset0:160 offset1:176
	ds_write2_b32 v150, v34, v38 offset0:32 offset1:48
	ds_write2_b32 v150, v35, v39 offset0:160 offset1:176
	ds_write2_b32 v151, v104, v108 offset0:64 offset1:80
	ds_write2_b32 v151, v105, v109 offset0:192 offset1:208
	ds_write2_b32 v150, v106, v110 offset0:64 offset1:80
	ds_write2_b32 v150, v107, v111 offset0:192 offset1:208
	ds_write2_b32 v151, v92, v100 offset0:96 offset1:112
	ds_write2_b32 v151, v93, v101 offset0:224 offset1:240
	ds_write2_b32 v150, v94, v102 offset0:96 offset1:112
	ds_write2_b32 v150, v95, v103 offset0:224 offset1:240
	ds_write2_b32 v149, v24, v28 offset1:16
	ds_write2_b32 v149, v25, v29 offset0:128 offset1:144
	ds_write2_b32 v148, v26, v30 offset1:16
	ds_write2_b32 v148, v27, v31 offset0:128 offset1:144
	ds_write2_b32 v149, v16, v20 offset0:32 offset1:48
	ds_write2_b32 v149, v17, v21 offset0:160 offset1:176
	ds_write2_b32 v148, v18, v22 offset0:32 offset1:48
	ds_write2_b32 v148, v19, v23 offset0:160 offset1:176
	ds_write2_b32 v149, v56, v60 offset0:64 offset1:80
	ds_write2_b32 v149, v57, v61 offset0:192 offset1:208
	ds_write2_b32 v148, v58, v62 offset0:64 offset1:80
	ds_write2_b32 v148, v59, v63 offset0:192 offset1:208
	ds_write2_b32 v149, v44, v72 offset0:96 offset1:112
	ds_write2_b32 v149, v45, v73 offset0:224 offset1:240
	ds_write2_b32 v148, v46, v74 offset0:96 offset1:112
	ds_write2_b32 v148, v47, v75 offset0:224 offset1:240
	ds_write2_b32 v147, v8, v12 offset1:16
	ds_write2_b32 v147, v9, v13 offset0:128 offset1:144
	ds_write2_b32 v146, v10, v14 offset1:16
	ds_write2_b32 v146, v11, v15 offset0:128 offset1:144
	ds_write2_b32 v147, v0, v4 offset0:32 offset1:48
	ds_write2_b32 v147, v1, v5 offset0:160 offset1:176
	ds_write2_b32 v146, v2, v6 offset0:32 offset1:48
	ds_write2_b32 v146, v3, v7 offset0:160 offset1:176
	ds_write2_b32 v147, v48, v64 offset0:64 offset1:80
	ds_write2_b32 v147, v49, v65 offset0:192 offset1:208
	ds_write2_b32 v146, v50, v66 offset0:64 offset1:80
	ds_write2_b32 v146, v51, v67 offset0:192 offset1:208
	ds_write2_b32 v147, v68, v76 offset0:96 offset1:112
	ds_write2_b32 v147, v69, v77 offset0:224 offset1:240
	ds_write2_b32 v146, v70, v78 offset0:96 offset1:112
	ds_write2_b32 v146, v71, v79 offset0:224 offset1:240

.LBB0_1072:
	s_andn2_b64 vcc, exec, s[2:3]
	s_cbranch_vccnz .LBB0_1067
	v_mov_b32_e32 v20, v190
	s_mulk_i32 s31, 0xfe
	v_mov_b32_e32 v1, v177
	v_ashrrev_i32_e32 v12, 3, v20
	v_add3_u32 v8, s31, -1, v12
	v_med3_i32 v0, v8, 0, v203
	v_mul_u32_u24_e32 v176, 0x880, v0
	v_add_u32_e32 v0, 64, v8
	v_med3_i32 v0, v0, 0, v203
	v_mul_u32_u24_e32 v0, 0x880, v0
	v_lshl_add_u64 v[2:3], s[8:9], 0, v[0:1]
	v_add_u32_e32 v1, 0x80, v8
	v_med3_i32 v1, v1, 0, v203
	v_mul_u32_u24_e32 v4, 0x880, v1
	v_add_u32_e32 v1, 0xc0, v8
	v_lshrrev_b32_e32 v21, 4, v20
	v_med3_i32 v1, v1, 0, v203
	v_xor_b32_e32 v18, v21, v20
	v_mul_u32_u24_e32 v8, 0x880, v1
	v_lshl_add_u32 v1, s30, 8, v12
	v_mov_b64_e32 v[14:15], s[12:13]
	v_mad_i64_i32 v[12:13], s[2:3], v1, s78, 0
	v_mad_i64_i32 v[14:15], s[2:3], v1, s78, v[14:15]
	v_lshlrev_b32_e32 v1, 4, v18
	v_mov_b32_e32 v5, v177
	v_mov_b32_e32 v9, v177
	v_and_b32_e32 v139, 15, v20
	v_and_b32_e32 v18, 0x70, v1
	v_bfe_u32 v140, v20, 4, 2
	v_bfe_u32 v1, v20, 1, 3
	v_lshl_add_u64 v[6:7], s[8:9], 0, v[4:5]
	v_lshl_add_u64 v[10:11], s[8:9], 0, v[8:9]
	v_lshlrev_b32_e32 v5, 7, v139
	v_bitop3_b32 v9, v21, v1, 3 bitop3:0x6c
	v_bitop3_b32 v1, v140, v1, 4 bitop3:0x36
	v_lshl_or_b32 v142, v1, 4, v5
	v_ashrrev_i32_e32 v1, 1, v20
	v_lshl_add_u32 v146, v20, 4, 0
	v_lshl_add_u64 v[16:17], s[8:9], 0, v[176:177]
	v_mov_b32_e32 v19, v177
	v_and_b32_e32 v141, 0xffffff80, v1
	v_and_or_b32 v141, v20, 64, v141
	v_readfirstlane_b32 s2, v146
	v_add_u32_e32 v1, 0x2000, v146
	v_lshl_add_u64 v[16:17], v[16:17], 0, v[18:19]
	s_mov_b32 m0, s2
	v_readfirstlane_b32 s2, v1
	v_add_u32_e32 v1, 0x4000, v146
	v_lshl_add_u64 v[2:3], v[2:3], 0, v[18:19]
	global_load_lds_dwordx4 v[16:17], off
	s_mov_b32 m0, s2
	v_readfirstlane_b32 s2, v1
	v_add_u32_e32 v1, 0x6000, v146
	v_lshl_add_u64 v[6:7], v[6:7], 0, v[18:19]
	global_load_lds_dwordx4 v[2:3], off
	s_mov_b32 m0, s2
	v_readfirstlane_b32 s2, v1
	v_add_u32_e32 v1, 0x8000, v146
	v_lshl_add_u64 v[10:11], v[10:11], 0, v[18:19]
	global_load_lds_dwordx4 v[6:7], off
	s_mov_b32 m0, s2
	v_readfirstlane_b32 s2, v1
	v_lshl_add_u64 v[14:15], v[14:15], 0, v[18:19]
	global_load_lds_dwordx4 v[10:11], off
	s_mov_b32 m0, s2
	s_mov_b64 s[2:3], 0x22000
	v_add_u32_e32 v1, 0xa000, v146
	v_lshl_add_u64 v[2:3], v[14:15], 0, s[2:3]
	v_readfirstlane_b32 s2, v1
	global_load_lds_dwordx4 v[14:15], off
	s_mov_b32 m0, s2
	s_mov_b64 s[2:3], 0x44000
	v_add_u32_e32 v1, 0xc000, v146
	global_load_lds_dwordx4 v[2:3], off
	v_lshl_add_u64 v[2:3], v[14:15], 0, s[2:3]
	v_readfirstlane_b32 s2, v1
	s_mov_b32 m0, s2
	s_mov_b64 s[2:3], 0x66000
	v_add_u32_e32 v1, 0xe000, v146
	global_load_lds_dwordx4 v[2:3], off
	v_lshl_add_u64 v[2:3], v[14:15], 0, s[2:3]
	v_readfirstlane_b32 s2, v1
	s_mov_b32 m0, s2
	v_bitop3_b32 v1, v21, 7, v20 bitop3:0x48
	global_load_lds_dwordx4 v[2:3], off
	v_lshl_or_b32 v143, v9, 4, v5
	v_lshlrev_b32_e32 v5, 4, v1
	v_or_b32_e32 v2, v5, v8
	v_mov_b32_e32 v3, v177
	v_bfe_u32 v138, v20, 7, 1
	v_or_b32_e32 v12, v12, v5
	v_lshl_add_u64 v[130:131], s[28:29], 0, v[2:3]
	v_or_b32_e32 v2, v5, v4
	v_or_b32_e32 v0, v5, v0
	v_mov_b32_e32 v1, v177
	v_or_b32_e32 v176, v5, v176
	v_mov_b32_e32 v108, 0
	s_mov_b32 s4, 0
	v_lshlrev_b32_e32 v144, 7, v141
	v_lshlrev_b32_e32 v145, 14, v138
	v_lshl_add_u64 v[128:129], s[10:11], 0, v[12:13]
	v_lshl_add_u64 v[132:133], s[28:29], 0, v[2:3]
	v_lshl_add_u64 v[134:135], s[28:29], 0, v[0:1]
	v_lshl_add_u64 v[136:137], s[28:29], 0, v[176:177]
	s_mov_b64 s[2:3], 0
	v_mov_b32_e32 v109, v108
	v_mov_b32_e32 v110, v108
	v_mov_b32_e32 v111, v108
	v_mov_b32_e32 v0, v108
	v_mov_b32_e32 v1, v108
	v_mov_b32_e32 v2, v108
	v_mov_b32_e32 v3, v108
	v_mov_b32_e32 v4, v108
	v_mov_b32_e32 v5, v108
	v_mov_b32_e32 v6, v108
	v_mov_b32_e32 v7, v108
	v_mov_b32_e32 v8, v108
	v_mov_b32_e32 v9, v108
	v_mov_b32_e32 v10, v108
	v_mov_b32_e32 v11, v108
	v_mov_b32_e32 v16, v108
	v_mov_b32_e32 v17, v108
	v_mov_b32_e32 v18, v108
	v_mov_b32_e32 v19, v108
	v_mov_b32_e32 v24, v108
	v_mov_b32_e32 v25, v108
	v_mov_b32_e32 v26, v108
	v_mov_b32_e32 v27, v108
	v_mov_b32_e32 v32, v108
	v_mov_b32_e32 v33, v108
	v_mov_b32_e32 v34, v108
	v_mov_b32_e32 v35, v108
	v_mov_b32_e32 v40, v108
	v_mov_b32_e32 v41, v108
	v_mov_b32_e32 v42, v108
	v_mov_b32_e32 v43, v108
	v_mov_b32_e32 v12, v108
	v_mov_b32_e32 v13, v108
	v_mov_b32_e32 v14, v108
	v_mov_b32_e32 v15, v108
	v_mov_b32_e32 v20, v108
	v_mov_b32_e32 v21, v108
	v_mov_b32_e32 v22, v108
	v_mov_b32_e32 v23, v108
	v_mov_b32_e32 v28, v108
	v_mov_b32_e32 v29, v108
	v_mov_b32_e32 v30, v108
	v_mov_b32_e32 v31, v108
	v_mov_b32_e32 v36, v108
	v_mov_b32_e32 v37, v108
	v_mov_b32_e32 v38, v108
	v_mov_b32_e32 v39, v108
	v_mov_b32_e32 v48, v108
	v_mov_b32_e32 v49, v108
	v_mov_b32_e32 v50, v108
	v_mov_b32_e32 v51, v108
	v_mov_b32_e32 v56, v108
	v_mov_b32_e32 v57, v108
	v_mov_b32_e32 v58, v108
	v_mov_b32_e32 v59, v108
	v_mov_b32_e32 v64, v108
	v_mov_b32_e32 v65, v108
	v_mov_b32_e32 v66, v108
	v_mov_b32_e32 v67, v108
	v_mov_b32_e32 v72, v108
	v_mov_b32_e32 v73, v108
	v_mov_b32_e32 v74, v108
	v_mov_b32_e32 v75, v108
	v_mov_b32_e32 v44, v108
	v_mov_b32_e32 v45, v108
	v_mov_b32_e32 v46, v108
	v_mov_b32_e32 v47, v108
	v_mov_b32_e32 v52, v108
	v_mov_b32_e32 v53, v108
	v_mov_b32_e32 v54, v108
	v_mov_b32_e32 v55, v108
	v_mov_b32_e32 v60, v108
	v_mov_b32_e32 v61, v108
	v_mov_b32_e32 v62, v108
	v_mov_b32_e32 v63, v108
	v_mov_b32_e32 v68, v108
	v_mov_b32_e32 v69, v108
	v_mov_b32_e32 v70, v108
	v_mov_b32_e32 v71, v108
	v_mov_b32_e32 v80, v108
	v_mov_b32_e32 v81, v108
	v_mov_b32_e32 v82, v108
	v_mov_b32_e32 v83, v108
	v_mov_b32_e32 v88, v108
	v_mov_b32_e32 v89, v108
	v_mov_b32_e32 v90, v108
	v_mov_b32_e32 v91, v108
	v_mov_b32_e32 v96, v108
	v_mov_b32_e32 v97, v108
	v_mov_b32_e32 v98, v108
	v_mov_b32_e32 v99, v108
	v_mov_b32_e32 v104, v108
	v_mov_b32_e32 v105, v108
	v_mov_b32_e32 v106, v108
	v_mov_b32_e32 v107, v108
	v_mov_b32_e32 v76, v108
	v_mov_b32_e32 v77, v108
	v_mov_b32_e32 v78, v108
	v_mov_b32_e32 v79, v108
	v_mov_b32_e32 v84, v108
	v_mov_b32_e32 v85, v108
	v_mov_b32_e32 v86, v108
	v_mov_b32_e32 v87, v108
	v_mov_b32_e32 v92, v108
	v_mov_b32_e32 v93, v108
	v_mov_b32_e32 v94, v108
	v_mov_b32_e32 v95, v108
	v_mov_b32_e32 v100, v108
	v_mov_b32_e32 v101, v108
	v_mov_b32_e32 v102, v108
	v_mov_b32_e32 v103, v108
	v_mov_b32_e32 v112, v108
	v_mov_b32_e32 v113, v108
	v_mov_b32_e32 v114, v108
	v_mov_b32_e32 v115, v108
	v_mov_b32_e32 v116, v108
	v_mov_b32_e32 v117, v108
	v_mov_b32_e32 v118, v108
	v_mov_b32_e32 v119, v108
	v_mov_b32_e32 v120, v108
	v_mov_b32_e32 v121, v108
	v_mov_b32_e32 v122, v108
	v_mov_b32_e32 v123, v108
	v_mov_b32_e32 v124, v108
	v_mov_b32_e32 v125, v108
	v_mov_b32_e32 v126, v108
	v_mov_b32_e32 v127, v108
.LBB0_1074:
	s_add_i32 s5, s4, 0x10000
	s_and_b32 s40, s5, 0x10000
	s_waitcnt vmcnt(0)
	s_barrier
	s_and_b32 s4, s4, 0x10000
	s_add_i32 s4, s4, 0
	v_add_u32_e32 v147, s4, v144
	v_add_u32_e32 v160, v147, v143
	ds_read_b128 v[148:151], v160
	ds_read_b128 v[152:155], v160 offset:2048
	ds_read_b128 v[156:159], v160 offset:4096
	ds_read_b128 v[170:173], v160 offset:6144
	v_add_u32_e32 v251, v147, v142
	v_add_u32_e32 v160, s4, v145
	v_add_u32_e32 v161, v160, v143
	ds_read_b128 v[178:181], v161 offset:32768
	ds_read_b128 v[182:185], v161 offset:34816
	ds_read_b128 v[186:189], v161 offset:36864
	ds_read_b128 v[192:195], v161 offset:38912
	v_add_u32_e32 v250, v160, v142
	ds_read_b128 v[216:219], v161 offset:40960
	ds_read_b128 v[220:223], v161 offset:43008
	ds_read_b128 v[224:227], v161 offset:45056
	ds_read_b128 v[228:231], v161 offset:47104
	v_add_u32_e32 v254, s40, v146
	v_add_u32_e32 v232, 0x2000, v254
	v_readfirstlane_b32 s40, v254
	v_lshl_add_u64 v[174:175], v[136:137], 0, s[2:3]
	s_mov_b32 m0, s40
	v_readfirstlane_b32 s40, v232
	v_add_u32_e32 v232, 0x4000, v254
	global_load_lds_dwordx4 v[174:175], off
	v_lshl_add_u64 v[174:175], v[134:135], 0, s[2:3]
	s_mov_b32 m0, s40
	s_waitcnt lgkmcnt(4)
	v_mfma_f32_16x16x32_bf16 v[124:127], v[148:151], v[178:181], v[124:127]
	ds_read_b128 v[198:201], v251
	v_mfma_f32_16x16x32_bf16 v[120:123], v[148:151], v[182:185], v[120:123]
	ds_read_b128 v[204:207], v251 offset:2048
	v_readfirstlane_b32 s40, v232
	v_add_u32_e32 v232, 0x6000, v254
	global_load_lds_dwordx4 v[174:175], off
	v_mfma_f32_16x16x32_bf16 v[116:119], v[148:151], v[186:189], v[116:119]
	ds_read_b128 v[208:211], v251 offset:4096
	v_lshl_add_u64 v[174:175], v[132:133], 0, s[2:3]
	s_mov_b32 m0, s40
	v_readfirstlane_b32 s40, v232
	v_mfma_f32_16x16x32_bf16 v[112:115], v[148:151], v[192:195], v[112:115]
	ds_read_b128 v[212:215], v251 offset:6144
	global_load_lds_dwordx4 v[174:175], off
	v_lshl_add_u64 v[174:175], v[130:131], 0, s[2:3]
	s_mov_b32 m0, s40
	v_mfma_f32_16x16x32_bf16 v[104:107], v[152:155], v[178:181], v[104:107]
	s_mov_b64 s[40:41], 0x770080
	global_load_lds_dwordx4 v[174:175], off
	v_lshl_add_u64 v[174:175], v[128:129], 0, s[2:3]
	v_mfma_f32_16x16x32_bf16 v[96:99], v[152:155], v[182:185], v[96:99]
	v_add_u32_e32 v253, 0x8000, v254
	v_lshl_add_u64 v[232:233], v[174:175], 0, s[40:41]
	v_readfirstlane_b32 s40, v253
	v_mfma_f32_16x16x32_bf16 v[88:91], v[152:155], v[186:189], v[88:91]
	s_mov_b32 m0, s40
	s_mov_b64 s[40:41], 0x792080
	v_add_u32_e32 v253, 0xa000, v254
	v_mfma_f32_16x16x32_bf16 v[80:83], v[152:155], v[192:195], v[80:83]
	global_load_lds_dwordx4 v[232:233], off
	v_lshl_add_u64 v[232:233], v[174:175], 0, s[40:41]
	v_readfirstlane_b32 s40, v253
	v_mfma_f32_16x16x32_bf16 v[72:75], v[156:159], v[178:181], v[72:75]
	s_mov_b32 m0, s40
	s_mov_b64 s[40:41], 0x7b4080
	v_add_u32_e32 v253, 0xc000, v254
	v_mfma_f32_16x16x32_bf16 v[64:67], v[156:159], v[182:185], v[64:67]
	global_load_lds_dwordx4 v[232:233], off
	v_lshl_add_u64 v[232:233], v[174:175], 0, s[40:41]
	v_readfirstlane_b32 s40, v253
	v_mfma_f32_16x16x32_bf16 v[56:59], v[156:159], v[186:189], v[56:59]
	s_mov_b32 m0, s40
	s_mov_b64 s[40:41], 0x7d6080
	v_add_u32_e32 v254, 0xe000, v254
	v_mfma_f32_16x16x32_bf16 v[48:51], v[156:159], v[192:195], v[48:51]
	v_lshl_add_u64 v[174:175], v[174:175], 0, s[40:41]
	v_readfirstlane_b32 s40, v254
	global_load_lds_dwordx4 v[232:233], off
	v_mfma_f32_16x16x32_bf16 v[40:43], v[170:173], v[178:181], v[40:43]
	s_mov_b32 m0, s40
	global_load_lds_dwordx4 v[174:175], off
	v_mfma_f32_16x16x32_bf16 v[32:35], v[170:173], v[182:185], v[32:35]
	v_mfma_f32_16x16x32_bf16 v[24:27], v[170:173], v[186:189], v[24:27]
	v_mfma_f32_16x16x32_bf16 v[16:19], v[170:173], v[192:195], v[16:19]
	s_waitcnt lgkmcnt(4)
	v_mfma_f32_16x16x32_bf16 v[100:103], v[148:151], v[216:219], v[100:103]
	v_mfma_f32_16x16x32_bf16 v[92:95], v[148:151], v[220:223], v[92:95]
	v_mfma_f32_16x16x32_bf16 v[84:87], v[148:151], v[224:227], v[84:87]
	ds_read_b128 v[178:181], v250 offset:32768
	v_mfma_f32_16x16x32_bf16 v[76:79], v[148:151], v[228:231], v[76:79]
	ds_read_b128 v[182:185], v250 offset:34816
	v_mfma_f32_16x16x32_bf16 v[68:71], v[152:155], v[216:219], v[68:71]
	ds_read_b128 v[186:189], v250 offset:36864
	v_mfma_f32_16x16x32_bf16 v[60:63], v[152:155], v[220:223], v[60:63]
	ds_read_b128 v[192:195], v250 offset:38912
	v_mfma_f32_16x16x32_bf16 v[52:55], v[152:155], v[224:227], v[52:55]
	v_mfma_f32_16x16x32_bf16 v[44:47], v[152:155], v[228:231], v[44:47]
	v_mfma_f32_16x16x32_bf16 v[36:39], v[156:159], v[216:219], v[36:39]
	v_mfma_f32_16x16x32_bf16 v[28:31], v[156:159], v[220:223], v[28:31]
	v_mfma_f32_16x16x32_bf16 v[20:23], v[156:159], v[224:227], v[20:23]
	v_mfma_f32_16x16x32_bf16 v[12:15], v[156:159], v[228:231], v[12:15]
	v_mfma_f32_16x16x32_bf16 v[8:11], v[170:173], v[216:219], v[8:11]
	v_mfma_f32_16x16x32_bf16 v[4:7], v[170:173], v[220:223], v[4:7]
	v_mfma_f32_16x16x32_bf16 v[0:3], v[170:173], v[224:227], v[0:3]
	v_mfma_f32_16x16x32_bf16 v[108:111], v[170:173], v[228:231], v[108:111]
	s_waitcnt lgkmcnt(0)
	v_mfma_f32_16x16x32_bf16 v[124:127], v[198:201], v[178:181], v[124:127]
	ds_read_b128 v[216:219], v250 offset:40960
	v_mfma_f32_16x16x32_bf16 v[120:123], v[198:201], v[182:185], v[120:123]
	ds_read_b128 v[220:223], v250 offset:43008
	v_mfma_f32_16x16x32_bf16 v[116:119], v[198:201], v[186:189], v[116:119]
	ds_read_b128 v[224:227], v250 offset:45056
	v_mfma_f32_16x16x32_bf16 v[112:115], v[198:201], v[192:195], v[112:115]
	ds_read_b128 v[228:231], v250 offset:47104
	v_mfma_f32_16x16x32_bf16 v[104:107], v[204:207], v[178:181], v[104:107]
	v_mfma_f32_16x16x32_bf16 v[96:99], v[204:207], v[182:185], v[96:99]
	v_mfma_f32_16x16x32_bf16 v[88:91], v[204:207], v[186:189], v[88:91]
	v_mfma_f32_16x16x32_bf16 v[80:83], v[204:207], v[192:195], v[80:83]
	v_mfma_f32_16x16x32_bf16 v[72:75], v[208:211], v[178:181], v[72:75]
	v_mfma_f32_16x16x32_bf16 v[64:67], v[208:211], v[182:185], v[64:67]
	v_mfma_f32_16x16x32_bf16 v[56:59], v[208:211], v[186:189], v[56:59]
	v_mfma_f32_16x16x32_bf16 v[48:51], v[208:211], v[192:195], v[48:51]
	v_mfma_f32_16x16x32_bf16 v[40:43], v[212:215], v[178:181], v[40:43]
	v_mfma_f32_16x16x32_bf16 v[32:35], v[212:215], v[182:185], v[32:35]
	v_mfma_f32_16x16x32_bf16 v[24:27], v[212:215], v[186:189], v[24:27]
	v_mfma_f32_16x16x32_bf16 v[16:19], v[212:215], v[192:195], v[16:19]
	s_waitcnt lgkmcnt(0)
	v_mfma_f32_16x16x32_bf16 v[100:103], v[198:201], v[216:219], v[100:103]
	v_mfma_f32_16x16x32_bf16 v[92:95], v[198:201], v[220:223], v[92:95]
	v_mfma_f32_16x16x32_bf16 v[84:87], v[198:201], v[224:227], v[84:87]
	v_mfma_f32_16x16x32_bf16 v[76:79], v[198:201], v[228:231], v[76:79]
	v_mfma_f32_16x16x32_bf16 v[68:71], v[204:207], v[216:219], v[68:71]
	v_mfma_f32_16x16x32_bf16 v[60:63], v[204:207], v[220:223], v[60:63]
	v_mfma_f32_16x16x32_bf16 v[52:55], v[204:207], v[224:227], v[52:55]
	v_mfma_f32_16x16x32_bf16 v[44:47], v[204:207], v[228:231], v[44:47]
	v_mfma_f32_16x16x32_bf16 v[36:39], v[208:211], v[216:219], v[36:39]
	v_mfma_f32_16x16x32_bf16 v[28:31], v[208:211], v[220:223], v[28:31]
	v_mfma_f32_16x16x32_bf16 v[20:23], v[208:211], v[224:227], v[20:23]
	v_mfma_f32_16x16x32_bf16 v[12:15], v[208:211], v[228:231], v[12:15]
	s_add_u32 s2, s2, 0x80
	s_addc_u32 s3, s3, 0
	s_cmpk_eq_i32 s2, 0x780
	s_mov_b32 s4, s5
	v_mfma_f32_16x16x32_bf16 v[8:11], v[212:215], v[216:219], v[8:11]
	v_mfma_f32_16x16x32_bf16 v[4:7], v[212:215], v[220:223], v[4:7]
	v_mfma_f32_16x16x32_bf16 v[0:3], v[212:215], v[224:227], v[0:3]
	v_mfma_f32_16x16x32_bf16 v[108:111], v[212:215], v[228:231], v[108:111]
	s_cbranch_scc0 .LBB0_1074
	s_add_i32 s2, 0, 0x10000
	v_add_u32_e32 v136, s2, v145
	v_add_u32_e32 v174, s2, v144
	v_add_u32_e32 v137, v136, v143
	v_add_u32_e32 v143, v174, v143
	s_waitcnt vmcnt(0)
	s_barrier
	ds_read_b128 v[128:131], v137 offset:38912
	ds_read_b128 v[132:135], v137 offset:36864
	ds_read_b128 v[146:149], v137 offset:34816
	ds_read_b128 v[150:153], v137 offset:32768
	ds_read_b128 v[154:157], v143 offset:6144
	ds_read_b128 v[158:161], v143 offset:4096
	ds_read_b128 v[170:173], v143 offset:2048
	ds_read_b128 v[178:181], v143
	s_waitcnt lgkmcnt(0)
	v_mfma_f32_16x16x32_bf16 v[124:127], v[178:181], v[150:153], v[124:127]
	v_mfma_f32_16x16x32_bf16 v[120:123], v[178:181], v[146:149], v[120:123]
	v_mfma_f32_16x16x32_bf16 v[116:119], v[178:181], v[132:135], v[116:119]
	v_mfma_f32_16x16x32_bf16 v[112:115], v[178:181], v[128:131], v[112:115]
	v_mfma_f32_16x16x32_bf16 v[104:107], v[170:173], v[150:153], v[104:107]
	v_mfma_f32_16x16x32_bf16 v[72:75], v[158:161], v[150:153], v[72:75]
	v_mfma_f32_16x16x32_bf16 v[64:67], v[158:161], v[146:149], v[64:67]
	v_mfma_f32_16x16x32_bf16 v[56:59], v[158:161], v[132:135], v[56:59]
	v_mfma_f32_16x16x32_bf16 v[48:51], v[158:161], v[128:131], v[48:51]
	v_mfma_f32_16x16x32_bf16 v[182:185], v[170:173], v[146:149], v[96:99]
	v_mfma_f32_16x16x32_bf16 v[186:189], v[170:173], v[132:135], v[88:91]
	v_mfma_f32_16x16x32_bf16 v[192:195], v[170:173], v[128:131], v[80:83]
	v_mfma_f32_16x16x32_bf16 v[150:153], v[154:157], v[150:153], v[40:43]
	v_mfma_f32_16x16x32_bf16 v[144:147], v[154:157], v[146:149], v[32:35]
	v_mfma_f32_16x16x32_bf16 v[132:135], v[154:157], v[132:135], v[24:27]
	v_mfma_f32_16x16x32_bf16 v[128:131], v[154:157], v[128:131], v[16:19]
	s_nop 2
	ds_read_b128 v[16:19], v137 offset:40960
	ds_read_b128 v[24:27], v137 offset:43008
	ds_read_b128 v[32:35], v137 offset:45056
	ds_read_b128 v[40:43], v137 offset:47104
	s_waitcnt lgkmcnt(0)
	v_mfma_f32_16x16x32_bf16 v[100:103], v[178:181], v[16:19], v[100:103]
	v_mfma_f32_16x16x32_bf16 v[92:95], v[178:181], v[24:27], v[92:95]
	v_mfma_f32_16x16x32_bf16 v[198:201], v[178:181], v[32:35], v[84:87]
	v_mfma_f32_16x16x32_bf16 v[76:79], v[178:181], v[40:43], v[76:79]
	v_mfma_f32_16x16x32_bf16 v[68:71], v[170:173], v[16:19], v[68:71]
	v_mfma_f32_16x16x32_bf16 v[60:63], v[170:173], v[24:27], v[60:63]
	v_mfma_f32_16x16x32_bf16 v[178:181], v[170:173], v[32:35], v[52:55]
	v_mfma_f32_16x16x32_bf16 v[44:47], v[170:173], v[40:43], v[44:47]
	v_mfma_f32_16x16x32_bf16 v[170:173], v[158:161], v[16:19], v[36:39]
	v_mfma_f32_16x16x32_bf16 v[204:207], v[158:161], v[24:27], v[28:31]
	v_mfma_f32_16x16x32_bf16 v[208:211], v[158:161], v[32:35], v[20:23]
	v_mfma_f32_16x16x32_bf16 v[158:161], v[158:161], v[40:43], v[12:15]
	v_mfma_f32_16x16x32_bf16 v[212:215], v[154:157], v[16:19], v[8:11]
	v_mfma_f32_16x16x32_bf16 v[216:219], v[154:157], v[24:27], v[4:7]
	v_mfma_f32_16x16x32_bf16 v[220:223], v[154:157], v[32:35], v[0:3]
	v_mfma_f32_16x16x32_bf16 v[154:157], v[154:157], v[40:43], v[108:111]
	s_nop 1
	v_add_u32_e32 v0, v174, v142
	v_add_u32_e32 v136, v136, v142
	ds_read_b128 v[108:111], v0
	ds_read_b128 v[224:227], v0 offset:2048
	ds_read_b128 v[228:231], v0 offset:4096
	ds_read_b128 v[232:235], v0 offset:6144
	ds_read_b128 v[0:3], v136 offset:32768
	ds_read_b128 v[4:7], v136 offset:34816
	ds_read_b128 v[236:239], v136 offset:36864
	ds_read_b128 v[240:243], v136 offset:38912
	s_waitcnt lgkmcnt(0)
	v_mfma_f32_16x16x32_bf16 v[88:91], v[108:111], v[0:3], v[124:127]
	v_mfma_f32_16x16x32_bf16 v[96:99], v[108:111], v[4:7], v[120:123]
	v_mfma_f32_16x16x32_bf16 v[80:83], v[108:111], v[236:239], v[116:119]
	v_mfma_f32_16x16x32_bf16 v[84:87], v[108:111], v[240:243], v[112:115]
	v_mfma_f32_16x16x32_bf16 v[40:43], v[224:227], v[0:3], v[104:107]
	v_mfma_f32_16x16x32_bf16 v[52:55], v[224:227], v[4:7], v[182:185]
	v_mfma_f32_16x16x32_bf16 v[32:35], v[224:227], v[236:239], v[186:189]
	v_mfma_f32_16x16x32_bf16 v[36:39], v[224:227], v[240:243], v[192:195]
	v_mfma_f32_16x16x32_bf16 v[24:27], v[228:231], v[0:3], v[72:75]
	v_mfma_f32_16x16x32_bf16 v[28:31], v[228:231], v[4:7], v[64:67]
	v_mfma_f32_16x16x32_bf16 v[16:19], v[228:231], v[236:239], v[56:59]
	v_mfma_f32_16x16x32_bf16 v[20:23], v[228:231], v[240:243], v[48:51]
	v_mfma_f32_16x16x32_bf16 v[8:11], v[232:235], v[0:3], v[150:153]
	v_mfma_f32_16x16x32_bf16 v[12:15], v[232:235], v[4:7], v[144:147]
	v_mfma_f32_16x16x32_bf16 v[0:3], v[232:235], v[236:239], v[132:135]
	v_mfma_f32_16x16x32_bf16 v[4:7], v[232:235], v[240:243], v[128:131]
	ds_read_b128 v[48:51], v136 offset:40960
	ds_read_b128 v[64:67], v136 offset:43008
	s_nop 0
	ds_read_b128 v[128:131], v136 offset:45056
	ds_read_b128 v[132:135], v136 offset:47104
	s_waitcnt lgkmcnt(0)
	v_mfma_f32_16x16x32_bf16 v[104:107], v[224:227], v[48:51], v[68:71]
	v_cmp_ne_u32_e32 vcc, 0, v138
	v_cmp_eq_u32_e64 s[2:3], 0, v138
	s_waitcnt vmcnt(0)
	v_lshl_or_b32 v68, v140, 2, v141
	v_lshl_add_u32 v69, v139, 2, 0
	v_mfma_f32_16x16x32_bf16 v[120:123], v[108:111], v[48:51], v[100:103]
	s_barrier
	v_mfma_f32_16x16x32_bf16 v[124:127], v[108:111], v[64:67], v[92:95]
	v_mfma_f32_16x16x32_bf16 v[112:115], v[108:111], v[128:131], v[198:201]
	v_mfma_f32_16x16x32_bf16 v[116:119], v[108:111], v[132:135], v[76:79]
	v_mfma_f32_16x16x32_bf16 v[108:111], v[224:227], v[64:67], v[60:63]
	v_mfma_f32_16x16x32_bf16 v[92:95], v[224:227], v[128:131], v[178:181]
	v_mfma_f32_16x16x32_bf16 v[100:103], v[224:227], v[132:135], v[44:47]
	s_nop 1
	v_lshl_add_u32 v178, v68, 9, v69
	v_add_u32_e32 v179, 0x400, v178
	v_add_u32_e32 v176, 0x2000, v178
	v_mfma_f32_16x16x32_bf16 v[56:59], v[228:231], v[48:51], v[170:173]
	v_add_u32_e32 v175, 0x2400, v178
	v_add_u32_e32 v174, 0x4000, v178
	v_mfma_f32_16x16x32_bf16 v[60:63], v[228:231], v[64:67], v[204:207]
	v_add_u32_e32 v173, 0x4400, v178
	v_add_u32_e32 v172, 0x6000, v178
	v_add_u32_e32 v171, 0x6400, v178
	v_mfma_f32_16x16x32_bf16 v[44:47], v[228:231], v[128:131], v[208:211]
	v_mfma_f32_16x16x32_bf16 v[72:75], v[228:231], v[132:135], v[158:161]
	v_mfma_f32_16x16x32_bf16 v[48:51], v[232:235], v[48:51], v[212:215]
	v_mfma_f32_16x16x32_bf16 v[64:67], v[232:235], v[64:67], v[216:219]
	v_mfma_f32_16x16x32_bf16 v[68:71], v[232:235], v[128:131], v[220:223]
	v_mfma_f32_16x16x32_bf16 v[76:79], v[232:235], v[132:135], v[154:157]
	s_and_saveexec_b64 s[4:5], s[2:3]
	s_cbranch_execz .LBB0_1077
	ds_write2_b32 v178, v88, v96 offset1:16
	ds_write2_b32 v178, v89, v97 offset0:128 offset1:144
	ds_write2_b32 v179, v90, v98 offset1:16
	ds_write2_b32 v179, v91, v99 offset0:128 offset1:144
	ds_write2_b32 v178, v80, v84 offset0:32 offset1:48
	ds_write2_b32 v178, v81, v85 offset0:160 offset1:176
	ds_write2_b32 v179, v82, v86 offset0:32 offset1:48
	ds_write2_b32 v179, v83, v87 offset0:160 offset1:176
	ds_write2_b32 v178, v120, v124 offset0:64 offset1:80
	ds_write2_b32 v178, v121, v125 offset0:192 offset1:208
	ds_write2_b32 v179, v122, v126 offset0:64 offset1:80
	ds_write2_b32 v179, v123, v127 offset0:192 offset1:208
	ds_write2_b32 v178, v112, v116 offset0:96 offset1:112
	ds_write2_b32 v178, v113, v117 offset0:224 offset1:240
	ds_write2_b32 v179, v114, v118 offset0:96 offset1:112
	ds_write2_b32 v179, v115, v119 offset0:224 offset1:240
	ds_write2_b32 v176, v40, v52 offset1:16
	ds_write2_b32 v176, v41, v53 offset0:128 offset1:144
	ds_write2_b32 v175, v42, v54 offset1:16
	ds_write2_b32 v175, v43, v55 offset0:128 offset1:144
	ds_write2_b32 v176, v32, v36 offset0:32 offset1:48
	ds_write2_b32 v176, v33, v37 offset0:160 offset1:176
	ds_write2_b32 v175, v34, v38 offset0:32 offset1:48
	ds_write2_b32 v175, v35, v39 offset0:160 offset1:176
	ds_write2_b32 v176, v104, v108 offset0:64 offset1:80
	ds_write2_b32 v176, v105, v109 offset0:192 offset1:208
	ds_write2_b32 v175, v106, v110 offset0:64 offset1:80
	ds_write2_b32 v175, v107, v111 offset0:192 offset1:208
	ds_write2_b32 v176, v92, v100 offset0:96 offset1:112
	ds_write2_b32 v176, v93, v101 offset0:224 offset1:240
	ds_write2_b32 v175, v94, v102 offset0:96 offset1:112
	ds_write2_b32 v175, v95, v103 offset0:224 offset1:240
	ds_write2_b32 v174, v24, v28 offset1:16
	ds_write2_b32 v174, v25, v29 offset0:128 offset1:144
	ds_write2_b32 v173, v26, v30 offset1:16
	ds_write2_b32 v173, v27, v31 offset0:128 offset1:144
	ds_write2_b32 v174, v16, v20 offset0:32 offset1:48
	ds_write2_b32 v174, v17, v21 offset0:160 offset1:176
	ds_write2_b32 v173, v18, v22 offset0:32 offset1:48
	ds_write2_b32 v173, v19, v23 offset0:160 offset1:176
	ds_write2_b32 v174, v56, v60 offset0:64 offset1:80
	ds_write2_b32 v174, v57, v61 offset0:192 offset1:208
	ds_write2_b32 v173, v58, v62 offset0:64 offset1:80
	ds_write2_b32 v173, v59, v63 offset0:192 offset1:208
	ds_write2_b32 v174, v44, v72 offset0:96 offset1:112
	ds_write2_b32 v174, v45, v73 offset0:224 offset1:240
	ds_write2_b32 v173, v46, v74 offset0:96 offset1:112
	ds_write2_b32 v173, v47, v75 offset0:224 offset1:240
	ds_write2_b32 v172, v8, v12 offset1:16
	ds_write2_b32 v172, v9, v13 offset0:128 offset1:144
	ds_write2_b32 v171, v10, v14 offset1:16
	ds_write2_b32 v171, v11, v15 offset0:128 offset1:144
	ds_write2_b32 v172, v0, v4 offset0:32 offset1:48
	ds_write2_b32 v172, v1, v5 offset0:160 offset1:176
	ds_write2_b32 v171, v2, v6 offset0:32 offset1:48
	ds_write2_b32 v171, v3, v7 offset0:160 offset1:176
	ds_write2_b32 v172, v48, v64 offset0:64 offset1:80
	ds_write2_b32 v172, v49, v65 offset0:192 offset1:208
	ds_write2_b32 v171, v50, v66 offset0:64 offset1:80
	ds_write2_b32 v171, v51, v67 offset0:192 offset1:208
	ds_write2_b32 v172, v68, v76 offset0:96 offset1:112
	ds_write2_b32 v172, v69, v77 offset0:224 offset1:240
	ds_write2_b32 v171, v70, v78 offset0:96 offset1:112
	ds_write2_b32 v171, v71, v79 offset0:224 offset1:240

.LBB0_1142:
	s_ashr_i32 s10, s2, 7
	s_mul_i32 s3, s10, 33
	s_bfe_u32 s11, s2, 0x50002
	s_add_i32 s13, s3, s11
	s_add_i32 s13, s13, 1
	v_mov_b32_e32 v14, v190
	s_lshl_b32 s17, s13, 8
	s_lshl_b32 s2, s2, 8
	s_and_b32 s12, s2, 0x300
	v_ashrrev_i32_e32 v15, 3, v14
	v_lshrrev_b32_e32 v16, 4, v14
	v_add_u32_e32 v18, s17, v15
	v_xor_b32_e32 v17, v16, v14
	v_add_u32_e32 v2, 64, v18
	v_mov_b64_e32 v[0:1], s[46:47]
	v_add_u32_e32 v4, 0x80, v18
	v_add_u32_e32 v6, 0xc0, v18
	v_add_u32_e32 v12, s12, v15
	v_mov_b64_e32 v[10:11], s[40:41]
	v_mad_i64_i32 v[2:3], s[2:3], v2, s87, v[0:1]
	v_mad_i64_i32 v[4:5], s[2:3], v4, s87, v[0:1]
	v_mad_i64_i32 v[6:7], s[2:3], v6, s87, v[0:1]
	v_mad_i64_i32 v[8:9], s[2:3], v12, s87, 0
	v_mad_i64_i32 v[10:11], s[2:3], v12, s87, v[10:11]
	v_mad_i64_i32 v[12:13], s[2:3], v18, s87, 0
	v_mad_i64_i32 v[0:1], s[2:3], v18, s87, v[0:1]
	v_lshlrev_b32_e32 v17, 4, v17
	v_lshl_add_u32 v150, v14, 4, 0
	v_and_b32_e32 v176, 0x70, v17
	v_readfirstlane_b32 s2, v150
	v_lshl_add_u64 v[0:1], v[0:1], 0, v[176:177]
	s_mov_b32 m0, s2
	v_lshl_add_u64 v[2:3], v[2:3], 0, v[176:177]
	global_load_lds_dwordx4 v[0:1], off
	v_add_u32_e32 v0, 0x2000, v150
	v_lshl_add_u64 v[4:5], v[4:5], 0, v[176:177]
	v_readfirstlane_b32 s2, v0
	v_add_u32_e32 v0, 0x4000, v150
	s_mov_b32 m0, s2
	v_readfirstlane_b32 s2, v0
	v_add_u32_e32 v0, 0x6000, v150
	global_load_lds_dwordx4 v[2:3], off
	s_mov_b32 m0, s2
	v_readfirstlane_b32 s2, v0
	v_add_u32_e32 v0, 0x8000, v150
	v_lshl_add_u64 v[6:7], v[6:7], 0, v[176:177]
	global_load_lds_dwordx4 v[4:5], off
	s_mov_b32 m0, s2
	v_readfirstlane_b32 s2, v0
	v_lshl_add_u64 v[10:11], v[10:11], 0, v[176:177]
	global_load_lds_dwordx4 v[6:7], off
	s_mov_b32 m0, s2
	s_mov_b64 s[2:3], 0x58000
	v_add_u32_e32 v2, 0xa000, v150
	v_lshl_add_u64 v[0:1], v[10:11], 0, s[2:3]
	v_readfirstlane_b32 s2, v2
	global_load_lds_dwordx4 v[10:11], off
	s_mov_b32 m0, s2
	s_mov_b64 s[2:3], 0xb0000
	v_add_u32_e32 v2, 0xc000, v150
	global_load_lds_dwordx4 v[0:1], off
	v_lshl_add_u64 v[0:1], v[10:11], 0, s[2:3]
	v_readfirstlane_b32 s2, v2
	s_mov_b32 m0, s2
	s_mov_b64 s[2:3], 0x108000
	v_add_u32_e32 v2, 0xe000, v150
	global_load_lds_dwordx4 v[0:1], off
	v_lshl_add_u64 v[0:1], v[10:11], 0, s[2:3]
	v_readfirstlane_b32 s2, v2
	s_mov_b32 m0, s2
	s_mulk_i32 s10, 0x2100
	global_load_lds_dwordx4 v[0:1], off
	s_lshl_b32 s18, s11, 8
	s_add_i32 s18, s18, s10
	v_bitop3_b32 v0, v16, 7, v14 bitop3:0x48
	v_add_u32_e32 v3, s18, v15
	v_lshlrev_b32_e32 v2, 4, v0
	v_add_u32_e32 v0, 0x140, v3
	v_mad_i64_i32 v[0:1], s[2:3], v0, s87, 0
	v_or_b32_e32 v0, v0, v2
	v_lshl_add_u64 v[130:131], s[50:51], 0, v[0:1]
	v_add_u32_e32 v0, 0x180, v3
	v_mad_i64_i32 v[0:1], s[2:3], v0, s87, 0
	v_and_b32_e32 v139, 15, v14
	v_bfe_u32 v140, v14, 4, 2
	v_bfe_u32 v17, v14, 1, 3
	v_or_b32_e32 v0, v0, v2
	v_lshlrev_b32_e32 v18, 7, v139
	v_bitop3_b32 v19, v16, v17, 3 bitop3:0x6c
	v_bitop3_b32 v17, v140, v17, 4 bitop3:0x36
	v_lshl_add_u64 v[132:133], s[50:51], 0, v[0:1]
	v_add_u32_e32 v0, 0x1c0, v3
	v_lshl_or_b32 v146, v17, 4, v18
	v_ashrrev_i32_e32 v17, 1, v14
	v_mad_i64_i32 v[0:1], s[2:3], v0, s87, 0
	v_bfe_u32 v138, v14, 7, 1
	v_and_b32_e32 v141, 0xffffff80, v17
	v_and_or_b32 v141, v14, 64, v141
	v_or_b32_e32 v12, v12, v2
	v_or_b32_e32 v0, v0, v2
	v_or_b32_e32 v8, v8, v2
	v_mov_b32_e32 v108, 0
	v_lshl_or_b32 v147, v19, 4, v18
	v_lshlrev_b32_e32 v149, 7, v141
	v_lshlrev_b32_e32 v148, 14, v138
	v_lshl_add_u64 v[128:129], s[50:51], 0, v[12:13]
	v_lshl_add_u64 v[134:135], s[50:51], 0, v[0:1]
	v_lshl_add_u64 v[136:137], s[8:9], 0, v[8:9]
	s_mov_b64 s[2:3], 0
	s_mov_b32 s10, 0
	v_mov_b32_e32 v109, v108
	v_mov_b32_e32 v110, v108
	v_mov_b32_e32 v111, v108
	v_mov_b32_e32 v0, v108
	v_mov_b32_e32 v1, v108
	v_mov_b32_e32 v2, v108
	v_mov_b32_e32 v3, v108
	v_mov_b32_e32 v4, v108
	v_mov_b32_e32 v5, v108
	v_mov_b32_e32 v6, v108
	v_mov_b32_e32 v7, v108
	v_mov_b32_e32 v8, v108
	v_mov_b32_e32 v9, v108
	v_mov_b32_e32 v10, v108
	v_mov_b32_e32 v11, v108
	v_mov_b32_e32 v16, v108
	v_mov_b32_e32 v17, v108
	v_mov_b32_e32 v18, v108
	v_mov_b32_e32 v19, v108
	v_mov_b32_e32 v24, v108
	v_mov_b32_e32 v25, v108
	v_mov_b32_e32 v26, v108
	v_mov_b32_e32 v27, v108
	v_mov_b32_e32 v32, v108
	v_mov_b32_e32 v33, v108
	v_mov_b32_e32 v34, v108
	v_mov_b32_e32 v35, v108
	v_mov_b32_e32 v40, v108
	v_mov_b32_e32 v41, v108
	v_mov_b32_e32 v42, v108
	v_mov_b32_e32 v43, v108
	v_mov_b32_e32 v12, v108
	v_mov_b32_e32 v13, v108
	v_mov_b32_e32 v14, v108
	v_mov_b32_e32 v15, v108
	v_mov_b32_e32 v20, v108
	v_mov_b32_e32 v21, v108
	v_mov_b32_e32 v22, v108
	v_mov_b32_e32 v23, v108
	v_mov_b32_e32 v28, v108
	v_mov_b32_e32 v29, v108
	v_mov_b32_e32 v30, v108
	v_mov_b32_e32 v31, v108
	v_mov_b32_e32 v36, v108
	v_mov_b32_e32 v37, v108
	v_mov_b32_e32 v38, v108
	v_mov_b32_e32 v39, v108
	v_mov_b32_e32 v48, v108
	v_mov_b32_e32 v49, v108
	v_mov_b32_e32 v50, v108
	v_mov_b32_e32 v51, v108
	v_mov_b32_e32 v56, v108
	v_mov_b32_e32 v57, v108
	v_mov_b32_e32 v58, v108
	v_mov_b32_e32 v59, v108
	v_mov_b32_e32 v64, v108
	v_mov_b32_e32 v65, v108
	v_mov_b32_e32 v66, v108
	v_mov_b32_e32 v67, v108
	v_mov_b32_e32 v72, v108
	v_mov_b32_e32 v73, v108
	v_mov_b32_e32 v74, v108
	v_mov_b32_e32 v75, v108
	v_mov_b32_e32 v44, v108
	v_mov_b32_e32 v45, v108
	v_mov_b32_e32 v46, v108
	v_mov_b32_e32 v47, v108
	v_mov_b32_e32 v52, v108
	v_mov_b32_e32 v53, v108
	v_mov_b32_e32 v54, v108
	v_mov_b32_e32 v55, v108
	v_mov_b32_e32 v60, v108
	v_mov_b32_e32 v61, v108
	v_mov_b32_e32 v62, v108
	v_mov_b32_e32 v63, v108
	v_mov_b32_e32 v68, v108
	v_mov_b32_e32 v69, v108
	v_mov_b32_e32 v70, v108
	v_mov_b32_e32 v71, v108
	v_mov_b32_e32 v80, v108
	v_mov_b32_e32 v81, v108
	v_mov_b32_e32 v82, v108
	v_mov_b32_e32 v83, v108
	v_mov_b32_e32 v88, v108
	v_mov_b32_e32 v89, v108
	v_mov_b32_e32 v90, v108
	v_mov_b32_e32 v91, v108
	v_mov_b32_e32 v96, v108
	v_mov_b32_e32 v97, v108
	v_mov_b32_e32 v98, v108
	v_mov_b32_e32 v99, v108
	v_mov_b32_e32 v104, v108
	v_mov_b32_e32 v105, v108
	v_mov_b32_e32 v106, v108
	v_mov_b32_e32 v107, v108
	v_mov_b32_e32 v76, v108
	v_mov_b32_e32 v77, v108
	v_mov_b32_e32 v78, v108
	v_mov_b32_e32 v79, v108
	v_mov_b32_e32 v84, v108
	v_mov_b32_e32 v85, v108
	v_mov_b32_e32 v86, v108
	v_mov_b32_e32 v87, v108
	v_mov_b32_e32 v92, v108
	v_mov_b32_e32 v93, v108
	v_mov_b32_e32 v94, v108
	v_mov_b32_e32 v95, v108
	v_mov_b32_e32 v100, v108
	v_mov_b32_e32 v101, v108
	v_mov_b32_e32 v102, v108
	v_mov_b32_e32 v103, v108
	v_mov_b32_e32 v112, v108
	v_mov_b32_e32 v113, v108
	v_mov_b32_e32 v114, v108
	v_mov_b32_e32 v115, v108
	v_mov_b32_e32 v116, v108
	v_mov_b32_e32 v117, v108
	v_mov_b32_e32 v118, v108
	v_mov_b32_e32 v119, v108
	v_mov_b32_e32 v120, v108
	v_mov_b32_e32 v121, v108
	v_mov_b32_e32 v122, v108
	v_mov_b32_e32 v123, v108
	v_mov_b32_e32 v124, v108
	v_mov_b32_e32 v125, v108
	v_mov_b32_e32 v126, v108
	v_mov_b32_e32 v127, v108
.LBB0_1143:
	s_add_i32 s11, s10, 0x10000
	s_and_b32 s19, s11, 0x10000
	s_waitcnt vmcnt(0)
	s_barrier
	s_and_b32 s10, s10, 0x10000
	s_add_i32 s10, s10, 0
	v_add_u32_e32 v151, s10, v149
	v_add_u32_e32 v164, v151, v147
	ds_read_b128 v[152:155], v164
	ds_read_b128 v[156:159], v164 offset:2048
	ds_read_b128 v[160:163], v164 offset:4096
	ds_read_b128 v[164:167], v164 offset:6144
	v_add_u32_e32 v251, v151, v146
	v_add_u32_e32 v176, s10, v148
	v_add_u32_e32 v186, v176, v147
	ds_read_b128 v[168:171], v186 offset:32768
	ds_read_b128 v[172:175], v186 offset:34816
	ds_read_b128 v[178:181], v186 offset:36864
	ds_read_b128 v[182:185], v186 offset:38912
	v_add_u32_e32 v250, v176, v146
	ds_read_b128 v[212:215], v186 offset:40960
	ds_read_b128 v[216:219], v186 offset:43008
	ds_read_b128 v[220:223], v186 offset:45056
	ds_read_b128 v[224:227], v186 offset:47104
	v_add_u32_e32 v254, s19, v150
	v_add_u32_e32 v228, 0x2000, v254
	v_readfirstlane_b32 s19, v254
	v_lshl_add_u64 v[188:189], v[128:129], 0, s[2:3]
	s_mov_b32 m0, s19
	v_readfirstlane_b32 s19, v228
	v_add_u32_e32 v228, 0x4000, v254
	global_load_lds_dwordx4 v[188:189], off
	v_lshl_add_u64 v[188:189], v[130:131], 0, s[2:3]
	s_mov_b32 m0, s19
	s_waitcnt lgkmcnt(4)
	v_mfma_f32_16x16x32_bf16 v[124:127], v[152:155], v[168:171], v[124:127]
	ds_read_b128 v[192:195], v251
	v_mfma_f32_16x16x32_bf16 v[120:123], v[152:155], v[172:175], v[120:123]
	ds_read_b128 v[198:201], v251 offset:2048
	v_readfirstlane_b32 s19, v228
	v_add_u32_e32 v228, 0x6000, v254
	global_load_lds_dwordx4 v[188:189], off
	v_mfma_f32_16x16x32_bf16 v[116:119], v[152:155], v[178:181], v[116:119]
	ds_read_b128 v[204:207], v251 offset:4096
	v_lshl_add_u64 v[188:189], v[132:133], 0, s[2:3]
	s_mov_b32 m0, s19
	v_readfirstlane_b32 s19, v228
	v_mfma_f32_16x16x32_bf16 v[112:115], v[152:155], v[182:185], v[112:115]
	ds_read_b128 v[208:211], v251 offset:6144
	global_load_lds_dwordx4 v[188:189], off
	v_lshl_add_u64 v[188:189], v[134:135], 0, s[2:3]
	s_mov_b32 m0, s19
	v_mfma_f32_16x16x32_bf16 v[104:107], v[156:159], v[168:171], v[104:107]
	v_add_u32_e32 v253, 0x8000, v254
	global_load_lds_dwordx4 v[188:189], off
	v_lshl_add_u64 v[188:189], v[136:137], 0, s[2:3]
	v_mfma_f32_16x16x32_bf16 v[96:99], v[156:159], v[172:175], v[96:99]
	s_mov_b64 s[20:21], 0x1320080
	v_readfirstlane_b32 s19, v253
	v_add_u32_e32 v253, 0xa000, v254
	v_mfma_f32_16x16x32_bf16 v[88:91], v[156:159], v[178:181], v[88:91]
	v_lshl_add_u64 v[228:229], v[188:189], 0, s[20:21]
	s_mov_b32 m0, s19
	s_mov_b64 s[20:21], 0x1378080
	v_mfma_f32_16x16x32_bf16 v[80:83], v[156:159], v[182:185], v[80:83]
	v_readfirstlane_b32 s19, v253
	v_add_u32_e32 v253, 0xc000, v254
	global_load_lds_dwordx4 v[228:229], off
	v_mfma_f32_16x16x32_bf16 v[72:75], v[160:163], v[168:171], v[72:75]
	v_lshl_add_u64 v[228:229], v[188:189], 0, s[20:21]
	s_mov_b32 m0, s19
	s_mov_b64 s[20:21], 0x13d0080
	v_mfma_f32_16x16x32_bf16 v[64:67], v[160:163], v[172:175], v[64:67]
	v_readfirstlane_b32 s19, v253
	v_add_u32_e32 v254, 0xe000, v254
	global_load_lds_dwordx4 v[228:229], off
	v_mfma_f32_16x16x32_bf16 v[56:59], v[160:163], v[178:181], v[56:59]
	v_lshl_add_u64 v[228:229], v[188:189], 0, s[20:21]
	s_mov_b32 m0, s19
	s_mov_b64 s[20:21], 0x1428080
	v_mfma_f32_16x16x32_bf16 v[48:51], v[160:163], v[182:185], v[48:51]
	v_readfirstlane_b32 s19, v254
	global_load_lds_dwordx4 v[228:229], off
	v_lshl_add_u64 v[188:189], v[188:189], 0, s[20:21]
	v_mfma_f32_16x16x32_bf16 v[40:43], v[164:167], v[168:171], v[40:43]
	s_mov_b32 m0, s19
	global_load_lds_dwordx4 v[188:189], off
	v_mfma_f32_16x16x32_bf16 v[32:35], v[164:167], v[172:175], v[32:35]
	v_mfma_f32_16x16x32_bf16 v[24:27], v[164:167], v[178:181], v[24:27]
	v_mfma_f32_16x16x32_bf16 v[16:19], v[164:167], v[182:185], v[16:19]
	s_waitcnt lgkmcnt(4)
	v_mfma_f32_16x16x32_bf16 v[100:103], v[152:155], v[212:215], v[100:103]
	v_mfma_f32_16x16x32_bf16 v[92:95], v[152:155], v[216:219], v[92:95]
	v_mfma_f32_16x16x32_bf16 v[84:87], v[152:155], v[220:223], v[84:87]
	ds_read_b128 v[168:171], v250 offset:32768
	v_mfma_f32_16x16x32_bf16 v[76:79], v[152:155], v[224:227], v[76:79]
	ds_read_b128 v[172:175], v250 offset:34816
	v_mfma_f32_16x16x32_bf16 v[68:71], v[156:159], v[212:215], v[68:71]
	ds_read_b128 v[178:181], v250 offset:36864
	v_mfma_f32_16x16x32_bf16 v[60:63], v[156:159], v[216:219], v[60:63]
	ds_read_b128 v[182:185], v250 offset:38912
	v_mfma_f32_16x16x32_bf16 v[52:55], v[156:159], v[220:223], v[52:55]
	v_mfma_f32_16x16x32_bf16 v[44:47], v[156:159], v[224:227], v[44:47]
	v_mfma_f32_16x16x32_bf16 v[36:39], v[160:163], v[212:215], v[36:39]
	v_mfma_f32_16x16x32_bf16 v[28:31], v[160:163], v[216:219], v[28:31]
	v_mfma_f32_16x16x32_bf16 v[20:23], v[160:163], v[220:223], v[20:23]
	v_mfma_f32_16x16x32_bf16 v[12:15], v[160:163], v[224:227], v[12:15]
	v_mfma_f32_16x16x32_bf16 v[8:11], v[164:167], v[212:215], v[8:11]
	v_mfma_f32_16x16x32_bf16 v[4:7], v[164:167], v[216:219], v[4:7]
	v_mfma_f32_16x16x32_bf16 v[0:3], v[164:167], v[220:223], v[0:3]
	v_mfma_f32_16x16x32_bf16 v[108:111], v[164:167], v[224:227], v[108:111]
	s_waitcnt lgkmcnt(0)
	v_mfma_f32_16x16x32_bf16 v[124:127], v[192:195], v[168:171], v[124:127]
	ds_read_b128 v[212:215], v250 offset:40960
	v_mfma_f32_16x16x32_bf16 v[120:123], v[192:195], v[172:175], v[120:123]
	ds_read_b128 v[216:219], v250 offset:43008
	v_mfma_f32_16x16x32_bf16 v[116:119], v[192:195], v[178:181], v[116:119]
	ds_read_b128 v[220:223], v250 offset:45056
	v_mfma_f32_16x16x32_bf16 v[112:115], v[192:195], v[182:185], v[112:115]
	ds_read_b128 v[224:227], v250 offset:47104
	v_mfma_f32_16x16x32_bf16 v[104:107], v[198:201], v[168:171], v[104:107]
	v_mfma_f32_16x16x32_bf16 v[96:99], v[198:201], v[172:175], v[96:99]
	v_mfma_f32_16x16x32_bf16 v[88:91], v[198:201], v[178:181], v[88:91]
	v_mfma_f32_16x16x32_bf16 v[80:83], v[198:201], v[182:185], v[80:83]
	v_mfma_f32_16x16x32_bf16 v[72:75], v[204:207], v[168:171], v[72:75]
	v_mfma_f32_16x16x32_bf16 v[64:67], v[204:207], v[172:175], v[64:67]
	v_mfma_f32_16x16x32_bf16 v[56:59], v[204:207], v[178:181], v[56:59]
	v_mfma_f32_16x16x32_bf16 v[48:51], v[204:207], v[182:185], v[48:51]
	v_mfma_f32_16x16x32_bf16 v[40:43], v[208:211], v[168:171], v[40:43]
	v_mfma_f32_16x16x32_bf16 v[32:35], v[208:211], v[172:175], v[32:35]
	v_mfma_f32_16x16x32_bf16 v[24:27], v[208:211], v[178:181], v[24:27]
	v_mfma_f32_16x16x32_bf16 v[16:19], v[208:211], v[182:185], v[16:19]
	s_waitcnt lgkmcnt(0)
	v_mfma_f32_16x16x32_bf16 v[100:103], v[192:195], v[212:215], v[100:103]
	v_mfma_f32_16x16x32_bf16 v[92:95], v[192:195], v[216:219], v[92:95]
	v_mfma_f32_16x16x32_bf16 v[84:87], v[192:195], v[220:223], v[84:87]
	v_mfma_f32_16x16x32_bf16 v[76:79], v[192:195], v[224:227], v[76:79]
	v_mfma_f32_16x16x32_bf16 v[68:71], v[198:201], v[212:215], v[68:71]
	v_mfma_f32_16x16x32_bf16 v[60:63], v[198:201], v[216:219], v[60:63]
	v_mfma_f32_16x16x32_bf16 v[52:55], v[198:201], v[220:223], v[52:55]
	v_mfma_f32_16x16x32_bf16 v[44:47], v[198:201], v[224:227], v[44:47]
	v_mfma_f32_16x16x32_bf16 v[36:39], v[204:207], v[212:215], v[36:39]
	v_mfma_f32_16x16x32_bf16 v[28:31], v[204:207], v[216:219], v[28:31]
	v_mfma_f32_16x16x32_bf16 v[20:23], v[204:207], v[220:223], v[20:23]
	v_mfma_f32_16x16x32_bf16 v[12:15], v[204:207], v[224:227], v[12:15]
	s_add_u32 s2, s2, 0x80
	s_addc_u32 s3, s3, 0
	s_cmpk_eq_i32 s2, 0x1580
	s_mov_b32 s10, s11
	v_mfma_f32_16x16x32_bf16 v[8:11], v[208:211], v[212:215], v[8:11]
	v_mfma_f32_16x16x32_bf16 v[4:7], v[208:211], v[216:219], v[4:7]
	v_mfma_f32_16x16x32_bf16 v[0:3], v[208:211], v[220:223], v[0:3]
	v_mfma_f32_16x16x32_bf16 v[108:111], v[208:211], v[224:227], v[108:111]
	s_cbranch_scc0 .LBB0_1143
	s_add_i32 s2, 0, 0x10000
	v_add_u32_e32 v136, s2, v149
	v_add_u32_e32 v137, v136, v147
	s_waitcnt vmcnt(0)
	s_barrier
	ds_read_b128 v[128:131], v137
	ds_read_b128 v[132:135], v137 offset:2048
	ds_read_b128 v[150:153], v137 offset:4096
	ds_read_b128 v[154:157], v137 offset:6144
	v_add_u32_e32 v137, s2, v148
	v_add_u32_e32 v147, v137, v147
	ds_read_b128 v[158:161], v147 offset:32768
	ds_read_b128 v[162:165], v147 offset:34816
	ds_read_b128 v[166:169], v147 offset:36864
	ds_read_b128 v[170:173], v147 offset:38912
	s_waitcnt lgkmcnt(0)
	v_mfma_f32_16x16x32_bf16 v[124:127], v[128:131], v[158:161], v[124:127]
	v_mfma_f32_16x16x32_bf16 v[120:123], v[128:131], v[162:165], v[120:123]
	v_mfma_f32_16x16x32_bf16 v[116:119], v[128:131], v[166:169], v[116:119]
	v_mfma_f32_16x16x32_bf16 v[112:115], v[128:131], v[170:173], v[112:115]
	v_mfma_f32_16x16x32_bf16 v[104:107], v[132:135], v[158:161], v[104:107]
	v_mfma_f32_16x16x32_bf16 v[72:75], v[150:153], v[158:161], v[72:75]
	v_mfma_f32_16x16x32_bf16 v[64:67], v[150:153], v[162:165], v[64:67]
	v_mfma_f32_16x16x32_bf16 v[56:59], v[150:153], v[166:169], v[56:59]
	v_mfma_f32_16x16x32_bf16 v[48:51], v[150:153], v[170:173], v[48:51]
	v_mfma_f32_16x16x32_bf16 v[178:181], v[132:135], v[162:165], v[96:99]
	v_mfma_f32_16x16x32_bf16 v[182:185], v[132:135], v[166:169], v[88:91]
	v_mfma_f32_16x16x32_bf16 v[186:189], v[132:135], v[170:173], v[80:83]
	v_mfma_f32_16x16x32_bf16 v[158:161], v[154:157], v[158:161], v[40:43]
	v_mfma_f32_16x16x32_bf16 v[162:165], v[154:157], v[162:165], v[32:35]
	v_mfma_f32_16x16x32_bf16 v[166:169], v[154:157], v[166:169], v[24:27]
	v_mfma_f32_16x16x32_bf16 v[170:173], v[154:157], v[170:173], v[16:19]
	s_nop 2
	ds_read_b128 v[16:19], v147 offset:40960
	ds_read_b128 v[24:27], v147 offset:43008
	ds_read_b128 v[32:35], v147 offset:45056
	ds_read_b128 v[40:43], v147 offset:47104
	s_waitcnt lgkmcnt(0)
	v_mfma_f32_16x16x32_bf16 v[100:103], v[128:131], v[16:19], v[100:103]
	v_mfma_f32_16x16x32_bf16 v[92:95], v[128:131], v[24:27], v[92:95]
	v_mfma_f32_16x16x32_bf16 v[192:195], v[128:131], v[32:35], v[84:87]
	v_mfma_f32_16x16x32_bf16 v[76:79], v[128:131], v[40:43], v[76:79]
	v_mfma_f32_16x16x32_bf16 v[68:71], v[132:135], v[16:19], v[68:71]
	v_mfma_f32_16x16x32_bf16 v[60:63], v[132:135], v[24:27], v[60:63]
	v_mfma_f32_16x16x32_bf16 v[128:131], v[132:135], v[32:35], v[52:55]
	v_mfma_f32_16x16x32_bf16 v[44:47], v[132:135], v[40:43], v[44:47]
	v_mfma_f32_16x16x32_bf16 v[132:135], v[150:153], v[16:19], v[36:39]
	v_mfma_f32_16x16x32_bf16 v[198:201], v[150:153], v[24:27], v[28:31]
	v_mfma_f32_16x16x32_bf16 v[204:207], v[150:153], v[32:35], v[20:23]
	v_mfma_f32_16x16x32_bf16 v[148:151], v[150:153], v[40:43], v[12:15]
	v_mfma_f32_16x16x32_bf16 v[208:211], v[154:157], v[16:19], v[8:11]
	v_mfma_f32_16x16x32_bf16 v[212:215], v[154:157], v[24:27], v[4:7]
	v_mfma_f32_16x16x32_bf16 v[216:219], v[154:157], v[32:35], v[0:3]
	v_mfma_f32_16x16x32_bf16 v[154:157], v[154:157], v[40:43], v[108:111]
	s_nop 1
	v_add_u32_e32 v0, v136, v146
	v_add_u32_e32 v136, v137, v146
	ds_read_b128 v[108:111], v0
	ds_read_b128 v[220:223], v0 offset:2048
	ds_read_b128 v[224:227], v0 offset:4096
	ds_read_b128 v[228:231], v0 offset:6144
	ds_read_b128 v[0:3], v136 offset:32768
	ds_read_b128 v[4:7], v136 offset:34816
	ds_read_b128 v[232:235], v136 offset:36864
	ds_read_b128 v[236:239], v136 offset:38912
	s_waitcnt lgkmcnt(0)
	v_mfma_f32_16x16x32_bf16 v[88:91], v[108:111], v[0:3], v[124:127]
	v_mfma_f32_16x16x32_bf16 v[96:99], v[108:111], v[4:7], v[120:123]
	v_mfma_f32_16x16x32_bf16 v[80:83], v[108:111], v[232:235], v[116:119]
	v_mfma_f32_16x16x32_bf16 v[84:87], v[108:111], v[236:239], v[112:115]
	v_mfma_f32_16x16x32_bf16 v[40:43], v[220:223], v[0:3], v[104:107]
	v_mfma_f32_16x16x32_bf16 v[52:55], v[220:223], v[4:7], v[178:181]
	v_mfma_f32_16x16x32_bf16 v[32:35], v[220:223], v[232:235], v[182:185]
	v_mfma_f32_16x16x32_bf16 v[36:39], v[220:223], v[236:239], v[186:189]
	v_mfma_f32_16x16x32_bf16 v[24:27], v[224:227], v[0:3], v[72:75]
	v_mfma_f32_16x16x32_bf16 v[28:31], v[224:227], v[4:7], v[64:67]
	v_mfma_f32_16x16x32_bf16 v[16:19], v[224:227], v[232:235], v[56:59]
	v_mfma_f32_16x16x32_bf16 v[20:23], v[224:227], v[236:239], v[48:51]
	v_mfma_f32_16x16x32_bf16 v[8:11], v[228:231], v[0:3], v[158:161]
	v_mfma_f32_16x16x32_bf16 v[12:15], v[228:231], v[4:7], v[162:165]
	v_mfma_f32_16x16x32_bf16 v[0:3], v[228:231], v[232:235], v[166:169]
	v_mfma_f32_16x16x32_bf16 v[4:7], v[228:231], v[236:239], v[170:173]
	ds_read_b128 v[48:51], v136 offset:40960
	ds_read_b128 v[64:67], v136 offset:43008
	ds_read_b128 v[158:161], v136 offset:45056
	ds_read_b128 v[162:165], v136 offset:47104
	s_waitcnt lgkmcnt(0)
	v_mfma_f32_16x16x32_bf16 v[104:107], v[220:223], v[48:51], v[68:71]
	v_cmp_ne_u32_e32 vcc, 0, v138
	v_cmp_eq_u32_e64 s[2:3], 0, v138
	s_waitcnt vmcnt(0)
	v_lshl_or_b32 v68, v140, 2, v141
	v_lshl_add_u32 v69, v139, 2, 0
	v_mfma_f32_16x16x32_bf16 v[120:123], v[108:111], v[48:51], v[100:103]
	v_lshl_add_u32 v152, v68, 9, v69
	v_add_u32_e32 v153, 0x400, v152
	v_add_u32_e32 v147, 0x6000, v152
	v_mfma_f32_16x16x32_bf16 v[124:127], v[108:111], v[64:67], v[92:95]
	v_add_u32_e32 v146, 0x6400, v152
	s_barrier
	v_mfma_f32_16x16x32_bf16 v[112:115], v[108:111], v[158:161], v[192:195]
	v_mfma_f32_16x16x32_bf16 v[116:119], v[108:111], v[162:165], v[76:79]
	v_mfma_f32_16x16x32_bf16 v[108:111], v[220:223], v[64:67], v[60:63]
	v_mfma_f32_16x16x32_bf16 v[92:95], v[220:223], v[158:161], v[128:131]
	v_mfma_f32_16x16x32_bf16 v[100:103], v[220:223], v[162:165], v[44:47]
	v_mfma_f32_16x16x32_bf16 v[56:59], v[224:227], v[48:51], v[132:135]
	v_mfma_f32_16x16x32_bf16 v[60:63], v[224:227], v[64:67], v[198:201]
	v_mfma_f32_16x16x32_bf16 v[44:47], v[224:227], v[158:161], v[204:207]
	v_mfma_f32_16x16x32_bf16 v[72:75], v[224:227], v[162:165], v[148:151]
	v_mfma_f32_16x16x32_bf16 v[48:51], v[228:231], v[48:51], v[208:211]
	s_nop 1
	v_add_u32_e32 v151, 0x2000, v152
	v_add_u32_e32 v150, 0x2400, v152
	v_add_u32_e32 v149, 0x4000, v152
	v_mfma_f32_16x16x32_bf16 v[64:67], v[228:231], v[64:67], v[212:215]
	v_add_u32_e32 v148, 0x4400, v152
	v_mfma_f32_16x16x32_bf16 v[68:71], v[228:231], v[158:161], v[216:219]
	v_mfma_f32_16x16x32_bf16 v[76:79], v[228:231], v[162:165], v[154:157]
	s_and_saveexec_b64 s[10:11], s[2:3]
	s_cbranch_execz .LBB0_1146
	ds_write2_b32 v152, v88, v96 offset1:16
	ds_write2_b32 v152, v89, v97 offset0:128 offset1:144
	ds_write2_b32 v153, v90, v98 offset1:16
	ds_write2_b32 v153, v91, v99 offset0:128 offset1:144
	ds_write2_b32 v152, v80, v84 offset0:32 offset1:48
	ds_write2_b32 v152, v81, v85 offset0:160 offset1:176
	ds_write2_b32 v153, v82, v86 offset0:32 offset1:48
	ds_write2_b32 v153, v83, v87 offset0:160 offset1:176
	ds_write2_b32 v152, v120, v124 offset0:64 offset1:80
	ds_write2_b32 v152, v121, v125 offset0:192 offset1:208
	ds_write2_b32 v153, v122, v126 offset0:64 offset1:80
	ds_write2_b32 v153, v123, v127 offset0:192 offset1:208
	ds_write2_b32 v152, v112, v116 offset0:96 offset1:112
	ds_write2_b32 v152, v113, v117 offset0:224 offset1:240
	ds_write2_b32 v153, v114, v118 offset0:96 offset1:112
	ds_write2_b32 v153, v115, v119 offset0:224 offset1:240
	ds_write2_b32 v151, v40, v52 offset1:16
	ds_write2_b32 v151, v41, v53 offset0:128 offset1:144
	ds_write2_b32 v150, v42, v54 offset1:16
	ds_write2_b32 v150, v43, v55 offset0:128 offset1:144
	ds_write2_b32 v151, v32, v36 offset0:32 offset1:48
	ds_write2_b32 v151, v33, v37 offset0:160 offset1:176
	ds_write2_b32 v150, v34, v38 offset0:32 offset1:48
	ds_write2_b32 v150, v35, v39 offset0:160 offset1:176
	ds_write2_b32 v151, v104, v108 offset0:64 offset1:80
	ds_write2_b32 v151, v105, v109 offset0:192 offset1:208
	ds_write2_b32 v150, v106, v110 offset0:64 offset1:80
	ds_write2_b32 v150, v107, v111 offset0:192 offset1:208
	ds_write2_b32 v151, v92, v100 offset0:96 offset1:112
	ds_write2_b32 v151, v93, v101 offset0:224 offset1:240
	ds_write2_b32 v150, v94, v102 offset0:96 offset1:112
	ds_write2_b32 v150, v95, v103 offset0:224 offset1:240
	ds_write2_b32 v149, v24, v28 offset1:16
	ds_write2_b32 v149, v25, v29 offset0:128 offset1:144
	ds_write2_b32 v148, v26, v30 offset1:16
	ds_write2_b32 v148, v27, v31 offset0:128 offset1:144
	ds_write2_b32 v149, v16, v20 offset0:32 offset1:48
	ds_write2_b32 v149, v17, v21 offset0:160 offset1:176
	ds_write2_b32 v148, v18, v22 offset0:32 offset1:48
	ds_write2_b32 v148, v19, v23 offset0:160 offset1:176
	ds_write2_b32 v149, v56, v60 offset0:64 offset1:80
	ds_write2_b32 v149, v57, v61 offset0:192 offset1:208
	ds_write2_b32 v148, v58, v62 offset0:64 offset1:80
	ds_write2_b32 v148, v59, v63 offset0:192 offset1:208
	ds_write2_b32 v149, v44, v72 offset0:96 offset1:112
	ds_write2_b32 v149, v45, v73 offset0:224 offset1:240
	ds_write2_b32 v148, v46, v74 offset0:96 offset1:112
	ds_write2_b32 v148, v47, v75 offset0:224 offset1:240
	ds_write2_b32 v147, v8, v12 offset1:16
	ds_write2_b32 v147, v9, v13 offset0:128 offset1:144
	ds_write2_b32 v146, v10, v14 offset1:16
	ds_write2_b32 v146, v11, v15 offset0:128 offset1:144
	ds_write2_b32 v147, v0, v4 offset0:32 offset1:48
	ds_write2_b32 v147, v1, v5 offset0:160 offset1:176
	ds_write2_b32 v146, v2, v6 offset0:32 offset1:48
	ds_write2_b32 v146, v3, v7 offset0:160 offset1:176
	ds_write2_b32 v147, v48, v64 offset0:64 offset1:80
	ds_write2_b32 v147, v49, v65 offset0:192 offset1:208
	ds_write2_b32 v146, v50, v66 offset0:64 offset1:80
	ds_write2_b32 v146, v51, v67 offset0:192 offset1:208
	ds_write2_b32 v147, v68, v76 offset0:96 offset1:112
	ds_write2_b32 v147, v69, v77 offset0:224 offset1:240
	ds_write2_b32 v146, v70, v78 offset0:96 offset1:112
	ds_write2_b32 v146, v71, v79 offset0:224 offset1:240
